# v58 + attention chunk loops: NaN-canonicalising self-max folded into the consumer max (120 VALU ops -> s_nop), identical results for non-NaN inputs
# speedup vs baseline: 1.0083x; 1.0083x over previous
.LBB0_658:
	s_barrier
	s_waitcnt vmcnt(11)
	ds_write_b128 v170, v[26:29]
	s_waitcnt vmcnt(10)
	ds_write_b128 v171, v[30:33]
	s_waitcnt vmcnt(9)
	ds_write_b128 v172, v[34:37] offset:17408
	s_waitcnt lgkmcnt(0)
	s_barrier
	ds_read_b128 v[106:109], v173
	ds_read_b128 v[134:137], v173 offset:8832
	ds_read_b128 v[114:117], v174
	s_waitcnt lgkmcnt(2)
	v_mfma_f32_16x16x32_bf16 v[110:113], v[106:109], v[2:5], 0
	s_add_i32 s45, s44, -3
	s_min_u32 s4, s45, s55
	s_lshl_b32 s4, s4, 6
	v_mfma_f32_16x16x32_bf16 v[106:109], v[106:109], v[14:17], 0
	s_addk_i32 s4, 0xff00
	s_and_b64 s[48:49], s[40:41], exec
	s_cselect_b32 s58, 0xc0, s4
	s_waitcnt lgkmcnt(0)
	v_mfma_f32_16x16x32_bf16 v[110:113], v[114:117], v[6:9], v[110:113]
	s_mul_i32 s52, s58, 0xc00
	s_lshl_b64 s[48:49], s[58:59], 11
	ds_read_b128 v[118:121], v174 offset:1088
	v_mfma_f32_16x16x32_bf16 v[106:109], v[114:117], v[18:21], v[106:109]
	ds_read_b128 v[114:117], v173 offset:128
	s_mul_hi_u32 s4, s58, 0xc00
	s_add_u32 s52, s42, s52
	s_waitcnt lgkmcnt(0)
	v_mfma_f32_16x16x32_bf16 v[122:125], v[114:117], v[10:13], v[110:113]
	s_nop 2
	ds_read_b128 v[110:113], v173 offset:1088
	ds_read_b128 v[130:133], v174 offset:8704
	s_addc_u32 s53, s43, s4
	v_lshl_add_u64 v[26:27], v[146:147], 1, s[52:53]
	v_lshl_add_u64 v[30:31], v[148:149], 1, s[52:53]
	v_lshl_add_u64 v[26:27], v[140:141], 1, v[26:27]
	v_lshl_add_u64 v[30:31], v[142:143], 1, v[30:31]
	v_lshl_add_u64 v[34:35], v[162:163], 0, s[48:49]
	global_load_dwordx4 v[26:29], v[26:27], off
	v_mfma_f32_16x16x32_bf16 v[106:109], v[114:117], v[22:25], v[106:109]
	global_load_dwordx4 v[30:33], v[30:31], off
	ds_read_b128 v[192:195], v174 offset:9792
	global_load_dwordx4 v[34:37], v[34:35], off
	s_waitcnt lgkmcnt(2)
	v_mfma_f32_16x16x32_bf16 v[114:117], v[110:113], v[2:5], 0
	s_nop 1
	v_max_f32_e32 v0, v124, v125
	v_mfma_f32_16x16x32_bf16 v[110:113], v[110:113], v[14:17], 0
	v_max3_f32 v0, v122, v123, v0
	v_mfma_f32_16x16x32_bf16 v[114:117], v[118:121], v[6:9], v[114:117]
	v_mfma_f32_16x16x32_bf16 v[110:113], v[118:121], v[18:21], v[110:113]
	ds_read_b128 v[118:121], v173 offset:1216
	s_waitcnt lgkmcnt(0)
	v_mfma_f32_16x16x32_bf16 v[126:129], v[118:121], v[10:13], v[114:117]
	s_nop 3
	ds_read_b128 v[114:117], v173 offset:8704
	s_nop 2
	s_nop 0
	v_mfma_f32_16x16x32_bf16 v[110:113], v[118:121], v[22:25], v[110:113]
	s_nop 0
	v_max_f32_e32 v164, v128, v129
	v_max3_f32 v164, v126, v127, v164
	s_waitcnt lgkmcnt(0)
	v_mfma_f32_16x16x32_bf16 v[118:121], v[114:117], v[2:5], 0
	v_max3_f32 v0, v0, s51, v164
	v_mfma_f32_16x16x32_bf16 v[114:117], v[114:117], v[14:17], 0
	v_mfma_f32_16x16x32_bf16 v[118:121], v[130:133], v[6:9], v[118:121]
	v_mfma_f32_16x16x32_bf16 v[114:117], v[130:133], v[18:21], v[114:117]
	v_mfma_f32_16x16x32_bf16 v[130:133], v[134:137], v[10:13], v[118:121]
	s_nop 5
	ds_read_b128 v[118:121], v173 offset:9792
	v_mfma_f32_16x16x32_bf16 v[114:117], v[134:137], v[22:25], v[114:117]
	s_nop 1
	v_max_f32_e32 v164, v132, v133
	s_waitcnt lgkmcnt(0)
	v_mfma_f32_16x16x32_bf16 v[134:137], v[118:121], v[2:5], 0
	v_max3_f32 v164, v130, v131, v164
	v_mfma_f32_16x16x32_bf16 v[118:121], v[118:121], v[14:17], 0
	v_mfma_f32_16x16x32_bf16 v[134:137], v[192:195], v[6:9], v[134:137]
	v_mfma_f32_16x16x32_bf16 v[118:121], v[192:195], v[18:21], v[118:121]
	ds_read_b128 v[192:195], v173 offset:9920
	s_waitcnt lgkmcnt(0)
	v_mfma_f32_16x16x32_bf16 v[134:137], v[192:195], v[10:13], v[134:137]
	s_nop 7
	s_nop 1
	v_max_f32_e32 v165, v136, v137
	v_max3_f32 v165, v134, v135, v165
	v_max3_f32 v0, v0, v164, v165
	ds_bpermute_b32 v164, v155, v0
	v_mfma_f32_16x16x32_bf16 v[118:121], v[192:195], v[22:25], v[118:121]
	s_waitcnt lgkmcnt(0)
	s_nop 0
	v_max_f32_e32 v0, v0, v164
	ds_bpermute_b32 v164, v176, v0
	s_waitcnt lgkmcnt(0)
	s_nop 0
	v_max_f32_e32 v0, v0, v164
	v_mul_f32_e32 v0, 0x3e16c740, v0
	v_add_f32_e32 v164, 0x41000000, v166
	v_cmp_gt_f32_e32 vcc, v0, v164
	s_cbranch_vccz .LBB0_660
	s_nop 0
	v_cndmask_b32_e32 v164, v166, v0, vcc
	v_sub_f32_e32 v0, v166, v164
	v_exp_f32_e32 v0, v0
	v_mov_b32_e32 v165, v167
	v_mov_b32_e32 v166, v164
	v_mul_f32_e32 v160, v160, v0
	v_pk_mul_f32 v[104:105], v[104:105], v[0:1] op_sel_hi:[1,0]
	v_pk_mul_f32 v[102:103], v[102:103], v[0:1] op_sel_hi:[1,0]
	v_pk_mul_f32 v[100:101], v[100:101], v[0:1] op_sel_hi:[1,0]
	v_pk_mul_f32 v[98:99], v[98:99], v[0:1] op_sel_hi:[1,0]
	v_pk_mul_f32 v[96:97], v[96:97], v[0:1] op_sel_hi:[1,0]
	v_pk_mul_f32 v[94:95], v[94:95], v[0:1] op_sel_hi:[1,0]
	v_pk_mul_f32 v[92:93], v[92:93], v[0:1] op_sel_hi:[1,0]
	v_pk_mul_f32 v[90:91], v[90:91], v[0:1] op_sel_hi:[1,0]
	s_branch .LBB0_661

.LBB0_661:
	v_fma_f32 v0, v122, s46, -v166
	v_exp_f32_e32 v122, v0
	v_fma_f32 v0, v123, s46, -v166
	v_exp_f32_e32 v168, v0
	v_fma_f32 v0, v124, s46, -v166
	v_exp_f32_e32 v123, v0
	v_fma_f32 v0, v125, s46, -v166
	v_exp_f32_e32 v169, v0
	v_fma_f32 v0, v126, s46, -v166
	v_exp_f32_e32 v124, v0
	v_fma_f32 v0, v127, s46, -v166
	v_exp_f32_e32 v192, v0
	v_fma_f32 v0, v128, s46, -v166
	v_exp_f32_e32 v125, v0
	v_fma_f32 v0, v129, s46, -v166
	v_exp_f32_e32 v193, v0
	v_pk_add_f32 v[126:127], v[122:123], v[168:169]
	s_nop 0
	v_add_f32_e32 v0, v126, v127
	v_pk_add_f32 v[126:127], v[124:125], v[192:193]
	v_add_f32_e32 v167, 0, v0
	v_pk_add_f32 v[194:195], v[126:127], v[126:127] op_sel_hi:[0,1]
	v_fma_f32 v126, v131, s46, -v166
	v_exp_f32_e32 v177, v126
	v_fma_f32 v126, v132, s46, -v166
	v_exp_f32_e32 v179, v126
	v_fma_f32 v126, v133, s46, -v166
	v_exp_f32_e32 v196, v126
	v_fma_f32 v126, v134, s46, -v166
	v_fma_f32 v0, v130, s46, -v166
	v_exp_f32_e32 v130, v126
	v_fma_f32 v126, v135, s46, -v166
	v_exp_f32_e32 v132, v126
	v_fma_f32 v126, v136, s46, -v166
	v_exp_f32_e32 v0, v0
	v_exp_f32_e32 v194, v126
	v_fma_f32 v126, v137, s46, -v166
	v_exp_f32_e32 v166, v126
	v_add_f32_e32 v131, v0, v177
	v_add_f32_e32 v133, v179, v196
	v_pk_add_f32 v[126:127], v[130:131], v[132:133]
	v_pk_add_f32 v[128:129], v[194:195], v[166:167]
	s_nop 0
	v_pk_add_f32 v[126:127], v[126:127], v[128:129]
	s_nop 0
	v_add_f32_e32 v126, v126, v127
	ds_bpermute_b32 v127, v155, v126
	s_nop 0
	s_waitcnt lgkmcnt(0)
	v_add_f32_e32 v126, v126, v127
	ds_bpermute_b32 v127, v176, v126
	s_waitcnt lgkmcnt(0)
	v_add_f32_e32 v126, v126, v127
	v_add_f32_e32 v160, v160, v126
	s_nop 1
	v_max_f32_e32 v126, v108, v109
	s_nop 0
	v_max_f32_e32 v127, v112, v113
	v_max3_f32 v126, v106, v107, v126
	v_max3_f32 v127, v110, v111, v127
	v_max3_f32 v126, v126, s51, v127
	s_nop 1
	v_max_f32_e32 v127, v116, v117
	s_nop 0
	v_max_f32_e32 v128, v120, v121
	v_max3_f32 v127, v114, v115, v127
	v_max3_f32 v128, v118, v119, v128
	v_max3_f32 v131, v126, v127, v128
	ds_bpermute_b32 v133, v155, v131
	v_cvt_pk_bf16_f32 v126, v122, v168
	v_cvt_pk_bf16_f32 v127, v123, v169
	v_cvt_pk_bf16_f32 v128, v124, v192
	v_cvt_pk_bf16_f32 v129, v125, v193
	s_waitcnt lgkmcnt(0)
	s_nop 0
	v_max_f32_e32 v131, v131, v133
	ds_bpermute_b32 v133, v176, v131
	v_cvt_pk_bf16_f32 v122, v0, v177
	v_cvt_pk_bf16_f32 v123, v179, v196
	v_cvt_pk_bf16_f32 v124, v130, v132
	v_add_f32_e32 v130, 0x41000000, v165
	s_waitcnt lgkmcnt(0)
	s_nop 0
	v_max_f32_e32 v0, v131, v133
	v_mul_f32_e32 v0, 0x3e16c740, v0
	v_cmp_gt_f32_e32 vcc, v0, v130
	v_cvt_pk_bf16_f32 v125, v194, v166
	s_cbranch_vccz .LBB0_663
	s_nop 0
	v_cndmask_b32_e32 v130, v165, v0, vcc
	v_sub_f32_e32 v0, v165, v130
	v_exp_f32_e32 v0, v0
	v_mov_b32_e32 v165, v130
	v_mul_f32_e32 v161, v161, v0
	v_pk_mul_f32 v[88:89], v[88:89], v[0:1] op_sel_hi:[1,0]
	v_pk_mul_f32 v[86:87], v[86:87], v[0:1] op_sel_hi:[1,0]
	v_pk_mul_f32 v[84:85], v[84:85], v[0:1] op_sel_hi:[1,0]
	v_pk_mul_f32 v[82:83], v[82:83], v[0:1] op_sel_hi:[1,0]
	v_pk_mul_f32 v[80:81], v[80:81], v[0:1] op_sel_hi:[1,0]
	v_pk_mul_f32 v[78:79], v[78:79], v[0:1] op_sel_hi:[1,0]
	v_pk_mul_f32 v[76:77], v[76:77], v[0:1] op_sel_hi:[1,0]
	v_pk_mul_f32 v[74:75], v[74:75], v[0:1] op_sel_hi:[1,0]
.LBB0_663:
	v_fma_f32 v0, v106, s46, -v165
	v_exp_f32_e32 v106, v0
	v_fma_f32 v0, v107, s46, -v165
	v_exp_f32_e32 v130, v0
	v_fma_f32 v0, v108, s46, -v165
	v_exp_f32_e32 v107, v0
	v_fma_f32 v0, v109, s46, -v165
	v_exp_f32_e32 v131, v0
	v_fma_f32 v0, v110, s46, -v165
	v_exp_f32_e32 v108, v0
	v_fma_f32 v0, v111, s46, -v165
	v_exp_f32_e32 v110, v0
	v_fma_f32 v0, v112, s46, -v165
	v_exp_f32_e32 v109, v0
	v_fma_f32 v0, v113, s46, -v165
	v_exp_f32_e32 v111, v0
	v_pk_add_f32 v[112:113], v[106:107], v[130:131]
	v_mov_b64_e32 v[168:169], v[164:165]
	v_add_f32_e32 v0, v112, v113
	v_pk_add_f32 v[112:113], v[108:109], v[110:111]
	v_add_f32_e32 v133, 0, v0
	v_pk_add_f32 v[134:135], v[112:113], v[112:113] op_sel_hi:[0,1]
	v_fma_f32 v112, v115, s46, -v165
	v_exp_f32_e32 v136, v112
	v_fma_f32 v112, v116, s46, -v165
	v_fma_f32 v113, v119, s46, -v165
	v_fma_f32 v0, v114, s46, -v165
	v_exp_f32_e32 v137, v112
	v_fma_f32 v112, v117, s46, -v165
	v_exp_f32_e32 v114, v113
	v_fma_f32 v113, v120, s46, -v165
	v_exp_f32_e32 v0, v0
	v_exp_f32_e32 v164, v112
	v_fma_f32 v112, v118, s46, -v165
	v_exp_f32_e32 v134, v113
	v_fma_f32 v113, v121, s46, -v165
	v_exp_f32_e32 v112, v112
	v_exp_f32_e32 v132, v113
	v_add_f32_e32 v113, v0, v136
	v_add_f32_e32 v115, v137, v164
	v_pk_add_f32 v[116:117], v[112:113], v[114:115]
	v_pk_add_f32 v[118:119], v[134:135], v[132:133]
	v_cvt_pk_bf16_f32 v106, v106, v130
	v_cvt_pk_bf16_f32 v107, v107, v131
	v_cvt_pk_bf16_f32 v108, v108, v110
	v_cvt_pk_bf16_f32 v109, v109, v111
	v_cvt_pk_bf16_f32 v110, v0, v136
	s_nop 0
	v_pk_add_f32 v[116:117], v[116:117], v[118:119]
	v_cvt_pk_bf16_f32 v111, v137, v164
	v_cvt_pk_bf16_f32 v112, v112, v114
	s_nop 0
	v_add_f32_e32 v113, v116, v117
	ds_bpermute_b32 v115, v155, v113
	s_waitcnt lgkmcnt(0)
	v_add_f32_e32 v113, v113, v115
	ds_bpermute_b32 v115, v176, v113
	s_waitcnt lgkmcnt(0)
	v_add_f32_e32 v113, v113, v115
	v_add_f32_e32 v161, v161, v113
	v_cvt_pk_bf16_f32 v113, v134, v132
	ds_read_b64_tr_b16 v[116:117], v175 offset:18560
	ds_read_b64_tr_b16 v[114:115], v175 offset:17408
	ds_read_b64_tr_b16 v[118:119], v175 offset:17440
	ds_read_b64_tr_b16 v[120:121], v175 offset:18592
	s_waitcnt lgkmcnt(2)
	v_mfma_f32_16x16x32_bf16 v[102:105], v[114:117], v[126:129], v[102:105]
	v_mfma_f32_16x16x32_bf16 v[114:117], v[114:117], v[106:109], v[86:89]
	s_waitcnt lgkmcnt(0)
	v_mfma_f32_16x16x32_bf16 v[98:101], v[118:121], v[126:129], v[98:101]
	v_mfma_f32_16x16x32_bf16 v[118:121], v[118:121], v[106:109], v[82:85]
	s_nop 2
	ds_read_b64_tr_b16 v[82:83], v175 offset:17472
	ds_read_b64_tr_b16 v[84:85], v175 offset:18624
	s_waitcnt lgkmcnt(0)
	v_mfma_f32_16x16x32_bf16 v[130:133], v[82:85], v[106:109], v[78:81]
	s_nop 2
	ds_read_b64_tr_b16 v[78:79], v175 offset:17504
	ds_read_b64_tr_b16 v[80:81], v175 offset:18656
	v_mfma_f32_16x16x32_bf16 v[94:97], v[82:85], v[126:129], v[94:97]
	s_waitcnt lgkmcnt(0)
	v_mfma_f32_16x16x32_bf16 v[90:93], v[78:81], v[126:129], v[90:93]
	v_mfma_f32_16x16x32_bf16 v[106:109], v[78:81], v[106:109], v[74:77]
	s_nop 2
	ds_read_b64_tr_b16 v[76:77], v175 offset:27776
	ds_read_b64_tr_b16 v[74:75], v175 offset:26624
	ds_read_b64_tr_b16 v[78:79], v175 offset:26656
	ds_read_b64_tr_b16 v[80:81], v175 offset:27808
	s_add_i32 s4, s44, -2
	s_min_u32 s4, s4, s55
	s_waitcnt lgkmcnt(2)
	v_mfma_f32_16x16x32_bf16 v[86:89], v[74:77], v[122:125], v[102:105]
	s_lshl_b32 s4, s4, 6
	s_addk_i32 s4, 0xff00
	s_and_b64 s[48:49], s[40:41], exec
	v_mfma_f32_16x16x32_bf16 v[102:105], v[74:77], v[110:113], v[114:117]
	ds_read_b64_tr_b16 v[74:75], v175 offset:26688
	ds_read_b64_tr_b16 v[76:77], v175 offset:27840
	s_nop 0
	ds_read_b64_tr_b16 v[114:115], v175 offset:26720
	ds_read_b64_tr_b16 v[116:117], v175 offset:27872
	s_waitcnt lgkmcnt(0)
	v_mfma_f32_16x16x32_bf16 v[82:85], v[78:81], v[122:125], v[98:101]
	s_barrier
	s_waitcnt vmcnt(11)
	ds_write_b128 v170, v[38:41]
	s_waitcnt vmcnt(10)
	ds_write_b128 v171, v[42:45]
	s_waitcnt vmcnt(9)
	ds_write_b128 v172, v[46:49] offset:17408
	v_mfma_f32_16x16x32_bf16 v[98:101], v[78:81], v[110:113], v[118:121]
	s_waitcnt lgkmcnt(0)
	s_barrier
	v_mfma_f32_16x16x32_bf16 v[78:81], v[74:77], v[122:125], v[94:97]
	ds_read_b128 v[134:137], v173 offset:8832
	s_cselect_b32 s58, 0xc0, s4
	s_mul_i32 s52, s58, 0xc00
	v_mfma_f32_16x16x32_bf16 v[94:97], v[74:77], v[110:113], v[130:133]
	s_lshl_b64 s[48:49], s[58:59], 11
	ds_read_b128 v[118:121], v174 offset:1088
	s_mul_hi_u32 s4, s58, 0xc00
	v_mfma_f32_16x16x32_bf16 v[74:77], v[114:117], v[122:125], v[90:93]
	s_add_u32 s52, s42, s52
	s_addc_u32 s53, s43, s4
	v_lshl_add_u64 v[38:39], v[146:147], 1, s[52:53]
	v_mfma_f32_16x16x32_bf16 v[90:93], v[114:117], v[110:113], v[106:109]
	ds_read_b128 v[114:117], v174
	v_lshl_add_u64 v[42:43], v[148:149], 1, s[52:53]
	v_lshl_add_u64 v[38:39], v[140:141], 1, v[38:39]
	ds_read_b128 v[106:109], v173
	s_waitcnt lgkmcnt(0)
	v_mfma_f32_16x16x32_bf16 v[110:113], v[106:109], v[2:5], 0
	v_lshl_add_u64 v[42:43], v[142:143], 1, v[42:43]
	v_lshl_add_u64 v[46:47], v[162:163], 0, s[48:49]
	global_load_dwordx4 v[38:41], v[38:39], off
	v_mfma_f32_16x16x32_bf16 v[106:109], v[106:109], v[14:17], 0
	global_load_dwordx4 v[42:45], v[42:43], off
	ds_read_b128 v[130:133], v174 offset:8704
	global_load_dwordx4 v[46:49], v[46:47], off
	v_mfma_f32_16x16x32_bf16 v[110:113], v[114:117], v[6:9], v[110:113]
	ds_read_b128 v[192:195], v174 offset:9792
	v_mfma_f32_16x16x32_bf16 v[106:109], v[114:117], v[18:21], v[106:109]
	ds_read_b128 v[114:117], v173 offset:128
	s_waitcnt lgkmcnt(0)
	v_mfma_f32_16x16x32_bf16 v[122:125], v[114:117], v[10:13], v[110:113]
	s_nop 2
	ds_read_b128 v[110:113], v173 offset:1088
	s_nop 3
	s_nop 0
	v_mfma_f32_16x16x32_bf16 v[106:109], v[114:117], v[22:25], v[106:109]
	s_nop 0
	v_max_f32_e32 v0, v124, v125
	v_max3_f32 v0, v122, v123, v0
	s_waitcnt lgkmcnt(0)
	v_mfma_f32_16x16x32_bf16 v[114:117], v[110:113], v[2:5], 0
	v_mfma_f32_16x16x32_bf16 v[110:113], v[110:113], v[14:17], 0
	v_mfma_f32_16x16x32_bf16 v[114:117], v[118:121], v[6:9], v[114:117]
	v_mfma_f32_16x16x32_bf16 v[110:113], v[118:121], v[18:21], v[110:113]
	ds_read_b128 v[118:121], v173 offset:1216
	s_waitcnt lgkmcnt(0)
	v_mfma_f32_16x16x32_bf16 v[126:129], v[118:121], v[10:13], v[114:117]
	s_nop 3
	ds_read_b128 v[114:117], v173 offset:8704
	s_nop 2
	s_nop 0
	v_mfma_f32_16x16x32_bf16 v[110:113], v[118:121], v[22:25], v[110:113]
	s_nop 0
	v_max_f32_e32 v164, v128, v129
	v_max3_f32 v164, v126, v127, v164
	s_waitcnt lgkmcnt(0)
	v_mfma_f32_16x16x32_bf16 v[118:121], v[114:117], v[2:5], 0
	v_max3_f32 v0, v0, s51, v164
	v_mfma_f32_16x16x32_bf16 v[114:117], v[114:117], v[14:17], 0
	v_mfma_f32_16x16x32_bf16 v[118:121], v[130:133], v[6:9], v[118:121]
	v_mfma_f32_16x16x32_bf16 v[114:117], v[130:133], v[18:21], v[114:117]
	v_mfma_f32_16x16x32_bf16 v[130:133], v[134:137], v[10:13], v[118:121]
	s_nop 5
	ds_read_b128 v[118:121], v173 offset:9792
	v_mfma_f32_16x16x32_bf16 v[114:117], v[134:137], v[22:25], v[114:117]
	s_nop 1
	v_max_f32_e32 v164, v132, v133
	s_waitcnt lgkmcnt(0)
	v_mfma_f32_16x16x32_bf16 v[134:137], v[118:121], v[2:5], 0
	v_max3_f32 v164, v130, v131, v164
	v_mfma_f32_16x16x32_bf16 v[118:121], v[118:121], v[14:17], 0
	v_mfma_f32_16x16x32_bf16 v[134:137], v[192:195], v[6:9], v[134:137]
	v_mfma_f32_16x16x32_bf16 v[118:121], v[192:195], v[18:21], v[118:121]
	ds_read_b128 v[192:195], v173 offset:9920
	s_waitcnt lgkmcnt(0)
	v_mfma_f32_16x16x32_bf16 v[134:137], v[192:195], v[10:13], v[134:137]
	s_nop 7
	s_nop 1
	v_max_f32_e32 v166, v136, v137
	v_max3_f32 v166, v134, v135, v166
	v_max3_f32 v0, v0, v164, v166
	ds_bpermute_b32 v164, v155, v0
	v_mfma_f32_16x16x32_bf16 v[118:121], v[192:195], v[22:25], v[118:121]
	s_waitcnt lgkmcnt(0)
	s_nop 0
	v_max_f32_e32 v0, v0, v164
	ds_bpermute_b32 v164, v176, v0
	s_waitcnt lgkmcnt(0)
	s_nop 0
	v_max_f32_e32 v0, v0, v164
	v_mul_f32_e32 v0, 0x3e16c740, v0
	v_add_f32_e32 v164, 0x41000000, v168
	v_cmp_gt_f32_e32 vcc, v0, v164
	s_cbranch_vccz .LBB0_665
	s_nop 0
	v_cndmask_b32_e32 v166, v168, v0, vcc
	v_sub_f32_e32 v0, v168, v166
	v_exp_f32_e32 v0, v0
	v_mov_b32_e32 v167, v169
	v_mov_b32_e32 v165, v169
	v_mov_b32_e32 v168, v166
	v_mul_f32_e32 v160, v160, v0
	v_pk_mul_f32 v[88:89], v[88:89], v[0:1] op_sel_hi:[1,0]
	v_pk_mul_f32 v[86:87], v[86:87], v[0:1] op_sel_hi:[1,0]
	v_pk_mul_f32 v[84:85], v[84:85], v[0:1] op_sel_hi:[1,0]
	v_pk_mul_f32 v[82:83], v[82:83], v[0:1] op_sel_hi:[1,0]
	v_pk_mul_f32 v[80:81], v[80:81], v[0:1] op_sel_hi:[1,0]
	v_pk_mul_f32 v[78:79], v[78:79], v[0:1] op_sel_hi:[1,0]
	v_pk_mul_f32 v[76:77], v[76:77], v[0:1] op_sel_hi:[1,0]
	v_pk_mul_f32 v[74:75], v[74:75], v[0:1] op_sel_hi:[1,0]
	s_branch .LBB0_666

.LBB0_666:
	v_fma_f32 v0, v122, s46, -v168
	v_exp_f32_e32 v122, v0
	v_fma_f32 v0, v123, s46, -v168
	v_exp_f32_e32 v192, v0
	v_fma_f32 v0, v124, s46, -v168
	v_exp_f32_e32 v123, v0
	v_fma_f32 v0, v125, s46, -v168
	v_exp_f32_e32 v193, v0
	v_fma_f32 v0, v126, s46, -v168
	v_exp_f32_e32 v124, v0
	v_fma_f32 v0, v127, s46, -v168
	v_exp_f32_e32 v194, v0
	v_fma_f32 v0, v128, s46, -v168
	v_exp_f32_e32 v125, v0
	v_fma_f32 v0, v129, s46, -v168
	v_exp_f32_e32 v195, v0
	v_pk_add_f32 v[126:127], v[122:123], v[192:193]
	s_nop 0
	v_add_f32_e32 v0, v126, v127
	v_pk_add_f32 v[126:127], v[124:125], v[194:195]
	v_add_f32_e32 v169, 0, v0
	v_pk_add_f32 v[196:197], v[126:127], v[126:127] op_sel_hi:[0,1]
	v_fma_f32 v126, v131, s46, -v168
	v_exp_f32_e32 v164, v126
	v_fma_f32 v126, v132, s46, -v168
	v_exp_f32_e32 v177, v126
	v_fma_f32 v126, v133, s46, -v168
	v_exp_f32_e32 v179, v126
	v_fma_f32 v126, v134, s46, -v168
	v_fma_f32 v0, v130, s46, -v168
	v_exp_f32_e32 v130, v126
	v_fma_f32 v126, v135, s46, -v168
	v_exp_f32_e32 v132, v126
	v_fma_f32 v126, v136, s46, -v168
	v_exp_f32_e32 v0, v0
	v_exp_f32_e32 v196, v126
	v_fma_f32 v126, v137, s46, -v168
	v_exp_f32_e32 v168, v126
	v_add_f32_e32 v131, v0, v164
	v_add_f32_e32 v133, v177, v179
	v_pk_add_f32 v[126:127], v[130:131], v[132:133]
	v_pk_add_f32 v[128:129], v[196:197], v[168:169]
	s_nop 0
	v_pk_add_f32 v[126:127], v[126:127], v[128:129]
	s_nop 0
	v_add_f32_e32 v126, v126, v127
	ds_bpermute_b32 v127, v155, v126
	s_nop 0
	s_waitcnt lgkmcnt(0)
	v_add_f32_e32 v126, v126, v127
	ds_bpermute_b32 v127, v176, v126
	s_waitcnt lgkmcnt(0)
	v_add_f32_e32 v126, v126, v127
	v_add_f32_e32 v160, v160, v126
	s_nop 1
	v_max_f32_e32 v126, v108, v109
	s_nop 0
	v_max_f32_e32 v127, v112, v113
	v_max3_f32 v126, v106, v107, v126
	v_max3_f32 v127, v110, v111, v127
	v_max3_f32 v126, v126, s51, v127
	s_nop 1
	v_max_f32_e32 v127, v116, v117
	s_nop 0
	v_max_f32_e32 v128, v120, v121
	v_max3_f32 v127, v114, v115, v127
	v_max3_f32 v128, v118, v119, v128
	v_max3_f32 v131, v126, v127, v128
	ds_bpermute_b32 v133, v155, v131
	v_cvt_pk_bf16_f32 v126, v122, v192
	v_cvt_pk_bf16_f32 v127, v123, v193
	v_cvt_pk_bf16_f32 v128, v124, v194
	v_cvt_pk_bf16_f32 v129, v125, v195
	s_waitcnt lgkmcnt(0)
	s_nop 0
	v_max_f32_e32 v131, v131, v133
	ds_bpermute_b32 v133, v176, v131
	v_cvt_pk_bf16_f32 v122, v0, v164
	v_cvt_pk_bf16_f32 v123, v177, v179
	v_cvt_pk_bf16_f32 v124, v130, v132
	v_add_f32_e32 v130, 0x41000000, v165
	s_waitcnt lgkmcnt(0)
	s_nop 0
	v_max_f32_e32 v0, v131, v133
	v_mul_f32_e32 v0, 0x3e16c740, v0
	v_cmp_gt_f32_e32 vcc, v0, v130
	v_cvt_pk_bf16_f32 v125, v196, v168
	s_cbranch_vccz .LBB0_668
	s_nop 0
	v_cndmask_b32_e32 v167, v165, v0, vcc
	v_sub_f32_e32 v0, v165, v167
	v_exp_f32_e32 v0, v0
	v_mov_b32_e32 v165, v167
	v_mul_f32_e32 v161, v161, v0
	v_pk_mul_f32 v[104:105], v[104:105], v[0:1] op_sel_hi:[1,0]
	v_pk_mul_f32 v[102:103], v[102:103], v[0:1] op_sel_hi:[1,0]
	v_pk_mul_f32 v[100:101], v[100:101], v[0:1] op_sel_hi:[1,0]
	v_pk_mul_f32 v[98:99], v[98:99], v[0:1] op_sel_hi:[1,0]
	v_pk_mul_f32 v[96:97], v[96:97], v[0:1] op_sel_hi:[1,0]
	v_pk_mul_f32 v[94:95], v[94:95], v[0:1] op_sel_hi:[1,0]
	v_pk_mul_f32 v[92:93], v[92:93], v[0:1] op_sel_hi:[1,0]
	v_pk_mul_f32 v[90:91], v[90:91], v[0:1] op_sel_hi:[1,0]
.LBB0_668:
	v_fma_f32 v0, v106, s46, -v165
	v_exp_f32_e32 v106, v0
	v_fma_f32 v0, v107, s46, -v165
	v_exp_f32_e32 v130, v0
	v_fma_f32 v0, v108, s46, -v165
	v_exp_f32_e32 v107, v0
	v_fma_f32 v0, v109, s46, -v165
	v_exp_f32_e32 v131, v0
	v_fma_f32 v0, v110, s46, -v165
	v_exp_f32_e32 v108, v0
	v_fma_f32 v0, v111, s46, -v165
	v_exp_f32_e32 v110, v0
	v_fma_f32 v0, v112, s46, -v165
	v_exp_f32_e32 v109, v0
	v_fma_f32 v0, v113, s46, -v165
	v_exp_f32_e32 v111, v0
	v_pk_add_f32 v[112:113], v[106:107], v[130:131]
	v_cvt_pk_bf16_f32 v106, v106, v130
	v_cvt_pk_bf16_f32 v107, v107, v131
	s_nop 0
	v_add_f32_e32 v0, v112, v113
	v_pk_add_f32 v[112:113], v[108:109], v[110:111]
	v_add_f32_e32 v133, 0, v0
	v_pk_add_f32 v[134:135], v[112:113], v[112:113] op_sel_hi:[0,1]
	v_fma_f32 v112, v115, s46, -v165
	v_exp_f32_e32 v136, v112
	v_fma_f32 v112, v116, s46, -v165
	v_fma_f32 v113, v119, s46, -v165
	v_fma_f32 v0, v114, s46, -v165
	v_exp_f32_e32 v137, v112
	v_fma_f32 v112, v117, s46, -v165
	v_exp_f32_e32 v114, v113
	v_fma_f32 v113, v120, s46, -v165
	v_exp_f32_e32 v0, v0
	v_exp_f32_e32 v164, v112
	v_fma_f32 v112, v118, s46, -v165
	v_exp_f32_e32 v134, v113
	v_fma_f32 v113, v121, s46, -v165
	v_exp_f32_e32 v112, v112
	v_exp_f32_e32 v132, v113
	v_add_f32_e32 v113, v0, v136
	v_add_f32_e32 v115, v137, v164
	v_pk_add_f32 v[116:117], v[112:113], v[114:115]
	v_pk_add_f32 v[118:119], v[134:135], v[132:133]
	v_cvt_pk_bf16_f32 v108, v108, v110
	v_cvt_pk_bf16_f32 v109, v109, v111
	v_cvt_pk_bf16_f32 v110, v0, v136
	v_cvt_pk_bf16_f32 v111, v137, v164
	v_cvt_pk_bf16_f32 v112, v112, v114
	s_nop 0
	v_pk_add_f32 v[116:117], v[116:117], v[118:119]
	s_nop 0
	v_add_f32_e32 v113, v116, v117
	ds_bpermute_b32 v115, v155, v113
	s_waitcnt lgkmcnt(0)
	v_add_f32_e32 v113, v113, v115
	ds_bpermute_b32 v115, v176, v113
	s_waitcnt lgkmcnt(0)
	v_add_f32_e32 v113, v113, v115
	v_add_f32_e32 v161, v161, v113
	v_cvt_pk_bf16_f32 v113, v134, v132
	ds_read_b64_tr_b16 v[116:117], v175 offset:18560
	ds_read_b64_tr_b16 v[114:115], v175 offset:17408
	ds_read_b64_tr_b16 v[118:119], v175 offset:17440
	ds_read_b64_tr_b16 v[120:121], v175 offset:18592
	s_waitcnt lgkmcnt(2)
	v_mfma_f32_16x16x32_bf16 v[86:89], v[114:117], v[126:129], v[86:89]
	v_mfma_f32_16x16x32_bf16 v[102:105], v[114:117], v[106:109], v[102:105]
	ds_read_b64_tr_b16 v[114:115], v175 offset:17472
	ds_read_b64_tr_b16 v[116:117], v175 offset:18624
	s_waitcnt lgkmcnt(0)
	v_mfma_f32_16x16x32_bf16 v[78:81], v[114:117], v[126:129], v[78:81]
	v_mfma_f32_16x16x32_bf16 v[94:97], v[114:117], v[106:109], v[94:97]
	ds_read_b64_tr_b16 v[114:115], v175 offset:17504
	ds_read_b64_tr_b16 v[116:117], v175 offset:18656
	v_mfma_f32_16x16x32_bf16 v[82:85], v[118:121], v[126:129], v[82:85]
	v_mfma_f32_16x16x32_bf16 v[98:101], v[118:121], v[106:109], v[98:101]
	s_waitcnt lgkmcnt(0)
	v_mfma_f32_16x16x32_bf16 v[74:77], v[114:117], v[126:129], v[74:77]
	v_mfma_f32_16x16x32_bf16 v[90:93], v[114:117], v[106:109], v[90:93]
	ds_read_b64_tr_b16 v[108:109], v175 offset:27776
	ds_read_b64_tr_b16 v[106:107], v175 offset:26624
	ds_read_b64_tr_b16 v[114:115], v175 offset:26656
	ds_read_b64_tr_b16 v[116:117], v175 offset:27808
	s_add_i32 s4, s44, -1
	s_min_u32 s4, s4, s55
	s_waitcnt lgkmcnt(2)
	v_mfma_f32_16x16x32_bf16 v[86:89], v[106:109], v[122:125], v[86:89]
	s_lshl_b32 s4, s4, 6
	s_addk_i32 s4, 0xff00
	s_and_b64 s[48:49], s[40:41], exec
	v_mfma_f32_16x16x32_bf16 v[102:105], v[106:109], v[110:113], v[102:105]
	ds_read_b64_tr_b16 v[106:107], v175 offset:26688
	ds_read_b64_tr_b16 v[108:109], v175 offset:27840
	s_cselect_b32 s58, 0xc0, s4
	s_mul_i32 s52, s58, 0xc00
	s_waitcnt lgkmcnt(0)
	v_mfma_f32_16x16x32_bf16 v[78:81], v[106:109], v[122:125], v[78:81]
	s_lshl_b64 s[48:49], s[58:59], 11
	s_mul_hi_u32 s4, s58, 0xc00
	s_add_u32 s52, s42, s52
	v_mfma_f32_16x16x32_bf16 v[94:97], v[106:109], v[110:113], v[94:97]
	ds_read_b64_tr_b16 v[106:107], v175 offset:26720
	ds_read_b64_tr_b16 v[108:109], v175 offset:27872
	s_waitcnt lgkmcnt(0)
	s_barrier
	v_mfma_f32_16x16x32_bf16 v[74:77], v[106:109], v[122:125], v[74:77]
	s_waitcnt vmcnt(11)
	ds_write_b128 v170, v[50:53]
	s_waitcnt vmcnt(10)
	ds_write_b128 v171, v[54:57]
	s_waitcnt vmcnt(9)
	ds_write_b128 v172, v[58:61] offset:17408
	s_waitcnt lgkmcnt(0)
	v_mfma_f32_16x16x32_bf16 v[90:93], v[106:109], v[110:113], v[90:93]
	s_barrier
	ds_read_b128 v[106:109], v173
	ds_read_b128 v[134:137], v173 offset:8832
	v_mfma_f32_16x16x32_bf16 v[82:85], v[114:117], v[122:125], v[82:85]
	ds_read_b128 v[118:121], v174 offset:1088
	s_addc_u32 s53, s43, s4
	v_lshl_add_u64 v[50:51], v[146:147], 1, s[52:53]
	v_mfma_f32_16x16x32_bf16 v[98:101], v[114:117], v[110:113], v[98:101]
	ds_read_b128 v[114:117], v174
	v_lshl_add_u64 v[54:55], v[148:149], 1, s[52:53]
	v_lshl_add_u64 v[50:51], v[140:141], 1, v[50:51]
	s_waitcnt lgkmcnt(3)
	v_mfma_f32_16x16x32_bf16 v[110:113], v[106:109], v[2:5], 0
	v_lshl_add_u64 v[54:55], v[142:143], 1, v[54:55]
	v_lshl_add_u64 v[58:59], v[162:163], 0, s[48:49]
	global_load_dwordx4 v[50:53], v[50:51], off
	v_mfma_f32_16x16x32_bf16 v[106:109], v[106:109], v[14:17], 0
	global_load_dwordx4 v[54:57], v[54:55], off
	ds_read_b128 v[130:133], v174 offset:8704
	global_load_dwordx4 v[58:61], v[58:59], off
	s_waitcnt lgkmcnt(1)
	v_mfma_f32_16x16x32_bf16 v[110:113], v[114:117], v[6:9], v[110:113]
	ds_read_b128 v[192:195], v174 offset:9792
	v_mfma_f32_16x16x32_bf16 v[106:109], v[114:117], v[18:21], v[106:109]
	ds_read_b128 v[114:117], v173 offset:128
	s_waitcnt lgkmcnt(0)
	v_mfma_f32_16x16x32_bf16 v[122:125], v[114:117], v[10:13], v[110:113]
	s_nop 2
	ds_read_b128 v[110:113], v173 offset:1088
	s_nop 3
	s_nop 0
	v_mfma_f32_16x16x32_bf16 v[106:109], v[114:117], v[22:25], v[106:109]
	s_nop 0
	v_max_f32_e32 v0, v124, v125
	v_max3_f32 v0, v122, v123, v0
	s_waitcnt lgkmcnt(0)
	v_mfma_f32_16x16x32_bf16 v[114:117], v[110:113], v[2:5], 0
	v_mfma_f32_16x16x32_bf16 v[110:113], v[110:113], v[14:17], 0
	v_mfma_f32_16x16x32_bf16 v[114:117], v[118:121], v[6:9], v[114:117]
	v_mfma_f32_16x16x32_bf16 v[110:113], v[118:121], v[18:21], v[110:113]
	ds_read_b128 v[118:121], v173 offset:1216
	s_waitcnt lgkmcnt(0)
	v_mfma_f32_16x16x32_bf16 v[126:129], v[118:121], v[10:13], v[114:117]
	s_nop 3
	ds_read_b128 v[114:117], v173 offset:8704
	s_nop 2
	s_nop 0
	v_mfma_f32_16x16x32_bf16 v[110:113], v[118:121], v[22:25], v[110:113]
	s_nop 0
	v_max_f32_e32 v164, v128, v129
	v_max3_f32 v164, v126, v127, v164
	s_waitcnt lgkmcnt(0)
	v_mfma_f32_16x16x32_bf16 v[118:121], v[114:117], v[2:5], 0
	v_max3_f32 v0, v0, s51, v164
	v_mfma_f32_16x16x32_bf16 v[114:117], v[114:117], v[14:17], 0
	v_mfma_f32_16x16x32_bf16 v[118:121], v[130:133], v[6:9], v[118:121]
	v_mfma_f32_16x16x32_bf16 v[114:117], v[130:133], v[18:21], v[114:117]
	v_mfma_f32_16x16x32_bf16 v[130:133], v[134:137], v[10:13], v[118:121]
	s_nop 5
	ds_read_b128 v[118:121], v173 offset:9792
	v_mfma_f32_16x16x32_bf16 v[114:117], v[134:137], v[22:25], v[114:117]
	s_nop 1
	v_max_f32_e32 v164, v132, v133
	s_waitcnt lgkmcnt(0)
	v_mfma_f32_16x16x32_bf16 v[134:137], v[118:121], v[2:5], 0
	v_max3_f32 v164, v130, v131, v164
	v_mfma_f32_16x16x32_bf16 v[118:121], v[118:121], v[14:17], 0
	v_mfma_f32_16x16x32_bf16 v[134:137], v[192:195], v[6:9], v[134:137]
	v_mfma_f32_16x16x32_bf16 v[118:121], v[192:195], v[18:21], v[118:121]
	ds_read_b128 v[192:195], v173 offset:9920
	s_waitcnt lgkmcnt(0)
	v_mfma_f32_16x16x32_bf16 v[134:137], v[192:195], v[10:13], v[134:137]
	s_nop 7
	s_nop 1
	v_max_f32_e32 v168, v136, v137
	v_max3_f32 v168, v134, v135, v168
	v_max3_f32 v0, v0, v164, v168
	ds_bpermute_b32 v164, v155, v0
	v_mfma_f32_16x16x32_bf16 v[118:121], v[192:195], v[22:25], v[118:121]
	s_waitcnt lgkmcnt(0)
	s_nop 0
	v_max_f32_e32 v0, v0, v164
	ds_bpermute_b32 v164, v176, v0
	s_waitcnt lgkmcnt(0)
	s_nop 0
	v_max_f32_e32 v0, v0, v164
	v_mul_f32_e32 v0, 0x3e16c740, v0
	v_add_f32_e32 v164, 0x41000000, v166
	v_cmp_gt_f32_e32 vcc, v0, v164
	s_cbranch_vccz .LBB0_670
	s_nop 0
	v_cndmask_b32_e32 v168, v166, v0, vcc
	v_sub_f32_e32 v0, v166, v168
	v_exp_f32_e32 v0, v0
	v_mov_b32_e32 v169, v167
	v_mov_b32_e32 v165, v167
	v_mov_b32_e32 v166, v168
	v_mul_f32_e32 v160, v160, v0
	v_pk_mul_f32 v[88:89], v[88:89], v[0:1] op_sel_hi:[1,0]
	v_pk_mul_f32 v[86:87], v[86:87], v[0:1] op_sel_hi:[1,0]
	v_pk_mul_f32 v[84:85], v[84:85], v[0:1] op_sel_hi:[1,0]
	v_pk_mul_f32 v[82:83], v[82:83], v[0:1] op_sel_hi:[1,0]
	v_pk_mul_f32 v[80:81], v[80:81], v[0:1] op_sel_hi:[1,0]
	v_pk_mul_f32 v[78:79], v[78:79], v[0:1] op_sel_hi:[1,0]
	v_pk_mul_f32 v[76:77], v[76:77], v[0:1] op_sel_hi:[1,0]
	v_pk_mul_f32 v[74:75], v[74:75], v[0:1] op_sel_hi:[1,0]
	s_branch .LBB0_671

.LBB0_671:
	v_fma_f32 v0, v122, s46, -v166
	v_exp_f32_e32 v122, v0
	v_fma_f32 v0, v123, s46, -v166
	v_exp_f32_e32 v192, v0
	v_fma_f32 v0, v124, s46, -v166
	v_exp_f32_e32 v123, v0
	v_fma_f32 v0, v125, s46, -v166
	v_exp_f32_e32 v193, v0
	v_fma_f32 v0, v126, s46, -v166
	v_exp_f32_e32 v124, v0
	v_fma_f32 v0, v127, s46, -v166
	v_exp_f32_e32 v194, v0
	v_fma_f32 v0, v128, s46, -v166
	v_exp_f32_e32 v125, v0
	v_fma_f32 v0, v129, s46, -v166
	v_exp_f32_e32 v195, v0
	v_pk_add_f32 v[126:127], v[122:123], v[192:193]
	s_nop 0
	v_add_f32_e32 v0, v126, v127
	v_pk_add_f32 v[126:127], v[124:125], v[194:195]
	v_add_f32_e32 v167, 0, v0
	v_pk_add_f32 v[196:197], v[126:127], v[126:127] op_sel_hi:[0,1]
	v_fma_f32 v126, v131, s46, -v166
	v_exp_f32_e32 v164, v126
	v_fma_f32 v126, v132, s46, -v166
	v_exp_f32_e32 v177, v126
	v_fma_f32 v126, v133, s46, -v166
	v_exp_f32_e32 v179, v126
	v_fma_f32 v126, v134, s46, -v166
	v_fma_f32 v0, v130, s46, -v166
	v_exp_f32_e32 v130, v126
	v_fma_f32 v126, v135, s46, -v166
	v_exp_f32_e32 v132, v126
	v_fma_f32 v126, v136, s46, -v166
	v_exp_f32_e32 v0, v0
	v_exp_f32_e32 v196, v126
	v_fma_f32 v126, v137, s46, -v166
	v_exp_f32_e32 v166, v126
	v_add_f32_e32 v131, v0, v164
	v_add_f32_e32 v133, v177, v179
	v_pk_add_f32 v[126:127], v[130:131], v[132:133]
	v_pk_add_f32 v[128:129], v[196:197], v[166:167]
	s_nop 0
	v_pk_add_f32 v[126:127], v[126:127], v[128:129]
	s_nop 0
	v_add_f32_e32 v126, v126, v127
	ds_bpermute_b32 v127, v155, v126
	s_nop 0
	s_waitcnt lgkmcnt(0)
	v_add_f32_e32 v126, v126, v127
	ds_bpermute_b32 v127, v176, v126
	s_waitcnt lgkmcnt(0)
	v_add_f32_e32 v126, v126, v127
	v_add_f32_e32 v160, v160, v126
	s_nop 1
	v_max_f32_e32 v126, v108, v109
	s_nop 0
	v_max_f32_e32 v127, v112, v113
	v_max3_f32 v126, v106, v107, v126
	v_max3_f32 v127, v110, v111, v127
	v_max3_f32 v126, v126, s51, v127
	s_nop 1
	v_max_f32_e32 v127, v116, v117
	s_nop 0
	v_max_f32_e32 v128, v120, v121
	v_max3_f32 v127, v114, v115, v127
	v_max3_f32 v128, v118, v119, v128
	v_max3_f32 v131, v126, v127, v128
	ds_bpermute_b32 v133, v155, v131
	v_cvt_pk_bf16_f32 v126, v122, v192
	v_cvt_pk_bf16_f32 v127, v123, v193
	v_cvt_pk_bf16_f32 v128, v124, v194
	v_cvt_pk_bf16_f32 v129, v125, v195
	s_waitcnt lgkmcnt(0)
	s_nop 0
	v_max_f32_e32 v131, v131, v133
	ds_bpermute_b32 v133, v176, v131
	v_cvt_pk_bf16_f32 v122, v0, v164
	v_cvt_pk_bf16_f32 v123, v177, v179
	v_cvt_pk_bf16_f32 v124, v130, v132
	v_add_f32_e32 v130, 0x41000000, v165
	s_waitcnt lgkmcnt(0)
	s_nop 0
	v_max_f32_e32 v0, v131, v133
	v_mul_f32_e32 v0, 0x3e16c740, v0
	v_cmp_gt_f32_e32 vcc, v0, v130
	v_cvt_pk_bf16_f32 v125, v196, v166
	s_cbranch_vccz .LBB0_673
	s_nop 0
	v_cndmask_b32_e32 v169, v165, v0, vcc
	v_sub_f32_e32 v0, v165, v169
	v_exp_f32_e32 v0, v0
	v_mov_b32_e32 v165, v169
	v_mul_f32_e32 v161, v161, v0
	v_pk_mul_f32 v[104:105], v[104:105], v[0:1] op_sel_hi:[1,0]
	v_pk_mul_f32 v[102:103], v[102:103], v[0:1] op_sel_hi:[1,0]
	v_pk_mul_f32 v[100:101], v[100:101], v[0:1] op_sel_hi:[1,0]
	v_pk_mul_f32 v[98:99], v[98:99], v[0:1] op_sel_hi:[1,0]
	v_pk_mul_f32 v[96:97], v[96:97], v[0:1] op_sel_hi:[1,0]
	v_pk_mul_f32 v[94:95], v[94:95], v[0:1] op_sel_hi:[1,0]
	v_pk_mul_f32 v[92:93], v[92:93], v[0:1] op_sel_hi:[1,0]
	v_pk_mul_f32 v[90:91], v[90:91], v[0:1] op_sel_hi:[1,0]
.LBB0_673:
	v_fma_f32 v0, v106, s46, -v165
	v_exp_f32_e32 v106, v0
	v_fma_f32 v0, v107, s46, -v165
	v_exp_f32_e32 v130, v0
	v_fma_f32 v0, v108, s46, -v165
	v_exp_f32_e32 v107, v0
	v_fma_f32 v0, v109, s46, -v165
	v_exp_f32_e32 v131, v0
	v_fma_f32 v0, v110, s46, -v165
	v_exp_f32_e32 v108, v0
	v_fma_f32 v0, v111, s46, -v165
	v_exp_f32_e32 v110, v0
	v_fma_f32 v0, v112, s46, -v165
	v_exp_f32_e32 v109, v0
	v_fma_f32 v0, v113, s46, -v165
	v_exp_f32_e32 v111, v0
	v_pk_add_f32 v[112:113], v[106:107], v[130:131]
	v_cvt_pk_bf16_f32 v106, v106, v130
	v_cvt_pk_bf16_f32 v107, v107, v131
	s_nop 0
	v_add_f32_e32 v0, v112, v113
	v_pk_add_f32 v[112:113], v[108:109], v[110:111]
	v_add_f32_e32 v133, 0, v0
	v_pk_add_f32 v[134:135], v[112:113], v[112:113] op_sel_hi:[0,1]
	v_fma_f32 v112, v115, s46, -v165
	v_exp_f32_e32 v136, v112
	v_fma_f32 v112, v116, s46, -v165
	v_fma_f32 v113, v119, s46, -v165
	v_fma_f32 v0, v114, s46, -v165
	v_exp_f32_e32 v137, v112
	v_fma_f32 v112, v117, s46, -v165
	v_exp_f32_e32 v114, v113
	v_fma_f32 v113, v120, s46, -v165
	v_exp_f32_e32 v0, v0
	v_exp_f32_e32 v164, v112
	v_fma_f32 v112, v118, s46, -v165
	v_exp_f32_e32 v134, v113
	v_fma_f32 v113, v121, s46, -v165
	v_exp_f32_e32 v112, v112
	v_exp_f32_e32 v132, v113
	v_add_f32_e32 v113, v0, v136
	v_add_f32_e32 v115, v137, v164
	v_pk_add_f32 v[116:117], v[112:113], v[114:115]
	v_pk_add_f32 v[118:119], v[134:135], v[132:133]
	v_cvt_pk_bf16_f32 v108, v108, v110
	v_cvt_pk_bf16_f32 v109, v109, v111
	v_cvt_pk_bf16_f32 v110, v0, v136
	v_cvt_pk_bf16_f32 v111, v137, v164
	v_cvt_pk_bf16_f32 v112, v112, v114
	s_nop 0
	v_pk_add_f32 v[116:117], v[116:117], v[118:119]
	s_nop 0
	v_add_f32_e32 v113, v116, v117
	ds_bpermute_b32 v115, v155, v113
	s_waitcnt lgkmcnt(0)
	v_add_f32_e32 v113, v113, v115
	ds_bpermute_b32 v115, v176, v113
	s_waitcnt lgkmcnt(0)
	v_add_f32_e32 v113, v113, v115
	v_add_f32_e32 v161, v161, v113
	v_cvt_pk_bf16_f32 v113, v134, v132
	ds_read_b64_tr_b16 v[116:117], v175 offset:18560
	ds_read_b64_tr_b16 v[114:115], v175 offset:17408
	ds_read_b64_tr_b16 v[118:119], v175 offset:17440
	ds_read_b64_tr_b16 v[120:121], v175 offset:18592
	s_waitcnt lgkmcnt(2)
	v_mfma_f32_16x16x32_bf16 v[86:89], v[114:117], v[126:129], v[86:89]
	v_mfma_f32_16x16x32_bf16 v[102:105], v[114:117], v[106:109], v[102:105]
	ds_read_b64_tr_b16 v[114:115], v175 offset:17472
	ds_read_b64_tr_b16 v[116:117], v175 offset:18624
	s_waitcnt lgkmcnt(0)
	v_mfma_f32_16x16x32_bf16 v[78:81], v[114:117], v[126:129], v[78:81]
	v_mfma_f32_16x16x32_bf16 v[94:97], v[114:117], v[106:109], v[94:97]
	ds_read_b64_tr_b16 v[114:115], v175 offset:17504
	ds_read_b64_tr_b16 v[116:117], v175 offset:18656
	v_mfma_f32_16x16x32_bf16 v[82:85], v[118:121], v[126:129], v[82:85]
	v_mfma_f32_16x16x32_bf16 v[98:101], v[118:121], v[106:109], v[98:101]
	s_waitcnt lgkmcnt(0)
	v_mfma_f32_16x16x32_bf16 v[74:77], v[114:117], v[126:129], v[74:77]
	v_mfma_f32_16x16x32_bf16 v[90:93], v[114:117], v[106:109], v[90:93]
	ds_read_b64_tr_b16 v[108:109], v175 offset:27776
	ds_read_b64_tr_b16 v[106:107], v175 offset:26624
	ds_read_b64_tr_b16 v[114:115], v175 offset:26656
	ds_read_b64_tr_b16 v[116:117], v175 offset:27808
	s_min_u32 s4, s44, s55
	s_lshl_b32 s4, s4, 6
	s_waitcnt lgkmcnt(2)
	v_mfma_f32_16x16x32_bf16 v[86:89], v[106:109], v[122:125], v[86:89]
	s_addk_i32 s4, 0xff00
	s_and_b64 s[48:49], s[40:41], exec
	s_cselect_b32 s58, 0xc0, s4
	v_mfma_f32_16x16x32_bf16 v[102:105], v[106:109], v[110:113], v[102:105]
	ds_read_b64_tr_b16 v[106:107], v175 offset:26688
	ds_read_b64_tr_b16 v[108:109], v175 offset:27840
	s_mul_i32 s52, s58, 0xc00
	s_lshl_b64 s[48:49], s[58:59], 11
	s_waitcnt lgkmcnt(0)
	v_mfma_f32_16x16x32_bf16 v[78:81], v[106:109], v[122:125], v[78:81]
	s_mul_hi_u32 s4, s58, 0xc00
	s_add_u32 s52, s42, s52
	s_addc_u32 s53, s43, s4
	v_mfma_f32_16x16x32_bf16 v[94:97], v[106:109], v[110:113], v[94:97]
	ds_read_b64_tr_b16 v[106:107], v175 offset:26720
	ds_read_b64_tr_b16 v[108:109], v175 offset:27872
	s_waitcnt lgkmcnt(0)
	s_barrier
	v_mfma_f32_16x16x32_bf16 v[74:77], v[106:109], v[122:125], v[74:77]
	s_waitcnt vmcnt(11)
	ds_write_b128 v170, v[62:65]
	s_waitcnt vmcnt(10)
	ds_write_b128 v171, v[66:69]
	s_waitcnt vmcnt(9)
	ds_write_b128 v172, v[70:73] offset:17408
	s_waitcnt lgkmcnt(0)
	v_mfma_f32_16x16x32_bf16 v[90:93], v[106:109], v[110:113], v[90:93]
	s_barrier
	ds_read_b128 v[106:109], v173
	ds_read_b128 v[134:137], v173 offset:8832
	v_mfma_f32_16x16x32_bf16 v[82:85], v[114:117], v[122:125], v[82:85]
	ds_read_b128 v[118:121], v174 offset:1088
	v_lshl_add_u64 v[62:63], v[146:147], 1, s[52:53]
	v_lshl_add_u64 v[66:67], v[148:149], 1, s[52:53]
	v_mfma_f32_16x16x32_bf16 v[98:101], v[114:117], v[110:113], v[98:101]
	ds_read_b128 v[114:117], v174
	v_lshl_add_u64 v[62:63], v[140:141], 1, v[62:63]
	v_lshl_add_u64 v[66:67], v[142:143], 1, v[66:67]
	s_waitcnt lgkmcnt(3)
	v_mfma_f32_16x16x32_bf16 v[110:113], v[106:109], v[2:5], 0
	v_lshl_add_u64 v[70:71], v[162:163], 0, s[48:49]
	global_load_dwordx4 v[62:65], v[62:63], off
	ds_read_b128 v[130:133], v174 offset:8704
	v_mfma_f32_16x16x32_bf16 v[106:109], v[106:109], v[14:17], 0
	global_load_dwordx4 v[66:69], v[66:67], off
	ds_read_b128 v[192:195], v174 offset:9792
	global_load_dwordx4 v[70:73], v[70:71], off
	s_waitcnt lgkmcnt(2)
	v_mfma_f32_16x16x32_bf16 v[110:113], v[114:117], v[6:9], v[110:113]
	v_mfma_f32_16x16x32_bf16 v[106:109], v[114:117], v[18:21], v[106:109]
	ds_read_b128 v[114:117], v173 offset:128
	s_waitcnt lgkmcnt(0)
	v_mfma_f32_16x16x32_bf16 v[122:125], v[114:117], v[10:13], v[110:113]
	s_nop 3
	ds_read_b128 v[110:113], v173 offset:1088
	s_nop 2
	s_nop 0
	v_mfma_f32_16x16x32_bf16 v[106:109], v[114:117], v[22:25], v[106:109]
	s_nop 0
	v_max_f32_e32 v0, v124, v125
	v_max3_f32 v0, v122, v123, v0
	s_waitcnt lgkmcnt(0)
	v_mfma_f32_16x16x32_bf16 v[114:117], v[110:113], v[2:5], 0
	v_mfma_f32_16x16x32_bf16 v[110:113], v[110:113], v[14:17], 0
	v_mfma_f32_16x16x32_bf16 v[114:117], v[118:121], v[6:9], v[114:117]
	v_mfma_f32_16x16x32_bf16 v[110:113], v[118:121], v[18:21], v[110:113]
	ds_read_b128 v[118:121], v173 offset:1216
	s_waitcnt lgkmcnt(0)
	v_mfma_f32_16x16x32_bf16 v[126:129], v[118:121], v[10:13], v[114:117]
	s_nop 3
	ds_read_b128 v[114:117], v173 offset:8704
	s_nop 2
	s_nop 0
	v_mfma_f32_16x16x32_bf16 v[110:113], v[118:121], v[22:25], v[110:113]
	s_nop 0
	v_max_f32_e32 v164, v128, v129
	v_max3_f32 v164, v126, v127, v164
	s_waitcnt lgkmcnt(0)
	v_mfma_f32_16x16x32_bf16 v[118:121], v[114:117], v[2:5], 0
	v_max3_f32 v0, v0, s51, v164
	v_mfma_f32_16x16x32_bf16 v[114:117], v[114:117], v[14:17], 0
	v_mfma_f32_16x16x32_bf16 v[118:121], v[130:133], v[6:9], v[118:121]
	v_mfma_f32_16x16x32_bf16 v[114:117], v[130:133], v[18:21], v[114:117]
	v_mfma_f32_16x16x32_bf16 v[130:133], v[134:137], v[10:13], v[118:121]
	s_nop 5
	ds_read_b128 v[118:121], v173 offset:9792
	v_mfma_f32_16x16x32_bf16 v[114:117], v[134:137], v[22:25], v[114:117]
	s_nop 1
	v_max_f32_e32 v164, v132, v133
	s_waitcnt lgkmcnt(0)
	v_mfma_f32_16x16x32_bf16 v[134:137], v[118:121], v[2:5], 0
	v_max3_f32 v164, v130, v131, v164
	v_mfma_f32_16x16x32_bf16 v[118:121], v[118:121], v[14:17], 0
	v_mfma_f32_16x16x32_bf16 v[134:137], v[192:195], v[6:9], v[134:137]
	v_mfma_f32_16x16x32_bf16 v[118:121], v[192:195], v[18:21], v[118:121]
	ds_read_b128 v[192:195], v173 offset:9920
	s_waitcnt lgkmcnt(0)
	v_mfma_f32_16x16x32_bf16 v[134:137], v[192:195], v[10:13], v[134:137]
	s_nop 7
	s_nop 1
	v_max_f32_e32 v166, v136, v137
	v_max3_f32 v166, v134, v135, v166
	v_max3_f32 v0, v0, v164, v166
	ds_bpermute_b32 v164, v155, v0
	v_mfma_f32_16x16x32_bf16 v[118:121], v[192:195], v[22:25], v[118:121]
	s_waitcnt lgkmcnt(0)
	s_nop 0
	v_max_f32_e32 v0, v0, v164
	ds_bpermute_b32 v164, v176, v0
	s_waitcnt lgkmcnt(0)
	s_nop 0
	v_max_f32_e32 v0, v0, v164
	v_mul_f32_e32 v0, 0x3e16c740, v0
	v_add_f32_e32 v164, 0x41000000, v168
	v_cmp_gt_f32_e32 vcc, v0, v164
	s_cbranch_vccz .LBB0_675
	s_nop 0
	v_cndmask_b32_e32 v166, v168, v0, vcc
	v_sub_f32_e32 v0, v168, v166
	v_exp_f32_e32 v0, v0
	v_mov_b32_e32 v167, v169
	v_mov_b32_e32 v165, v169
	v_mov_b32_e32 v168, v166
	v_mul_f32_e32 v160, v160, v0
	v_pk_mul_f32 v[88:89], v[88:89], v[0:1] op_sel_hi:[1,0]
	v_pk_mul_f32 v[86:87], v[86:87], v[0:1] op_sel_hi:[1,0]
	v_pk_mul_f32 v[84:85], v[84:85], v[0:1] op_sel_hi:[1,0]
	v_pk_mul_f32 v[82:83], v[82:83], v[0:1] op_sel_hi:[1,0]
	v_pk_mul_f32 v[80:81], v[80:81], v[0:1] op_sel_hi:[1,0]
	v_pk_mul_f32 v[78:79], v[78:79], v[0:1] op_sel_hi:[1,0]
	v_pk_mul_f32 v[76:77], v[76:77], v[0:1] op_sel_hi:[1,0]
	v_pk_mul_f32 v[74:75], v[74:75], v[0:1] op_sel_hi:[1,0]
	s_branch .LBB0_676

.LBB0_676:
	v_fma_f32 v0, v122, s46, -v168
	v_exp_f32_e32 v122, v0
	v_fma_f32 v0, v123, s46, -v168
	v_exp_f32_e32 v192, v0
	v_fma_f32 v0, v124, s46, -v168
	v_exp_f32_e32 v123, v0
	v_fma_f32 v0, v125, s46, -v168
	v_exp_f32_e32 v193, v0
	v_fma_f32 v0, v126, s46, -v168
	v_exp_f32_e32 v124, v0
	v_fma_f32 v0, v127, s46, -v168
	v_exp_f32_e32 v194, v0
	v_fma_f32 v0, v128, s46, -v168
	v_exp_f32_e32 v125, v0
	v_fma_f32 v0, v129, s46, -v168
	v_exp_f32_e32 v195, v0
	v_pk_add_f32 v[126:127], v[122:123], v[192:193]
	s_nop 0
	v_add_f32_e32 v0, v126, v127
	v_pk_add_f32 v[126:127], v[124:125], v[194:195]
	v_add_f32_e32 v169, 0, v0
	v_pk_add_f32 v[196:197], v[126:127], v[126:127] op_sel_hi:[0,1]
	v_fma_f32 v126, v131, s46, -v168
	v_exp_f32_e32 v164, v126
	v_fma_f32 v126, v132, s46, -v168
	v_exp_f32_e32 v177, v126
	v_fma_f32 v126, v133, s46, -v168
	v_exp_f32_e32 v179, v126
	v_fma_f32 v126, v134, s46, -v168
	v_fma_f32 v0, v130, s46, -v168
	v_exp_f32_e32 v130, v126
	v_fma_f32 v126, v135, s46, -v168
	v_exp_f32_e32 v132, v126
	v_fma_f32 v126, v136, s46, -v168
	v_exp_f32_e32 v0, v0
	v_exp_f32_e32 v196, v126
	v_fma_f32 v126, v137, s46, -v168
	v_exp_f32_e32 v168, v126
	v_add_f32_e32 v131, v0, v164
	v_add_f32_e32 v133, v177, v179
	v_pk_add_f32 v[126:127], v[130:131], v[132:133]
	v_pk_add_f32 v[128:129], v[196:197], v[168:169]
	s_nop 0
	v_pk_add_f32 v[126:127], v[126:127], v[128:129]
	s_nop 0
	v_add_f32_e32 v126, v126, v127
	ds_bpermute_b32 v127, v155, v126
	s_nop 0
	s_waitcnt lgkmcnt(0)
	v_add_f32_e32 v126, v126, v127
	ds_bpermute_b32 v127, v176, v126
	s_waitcnt lgkmcnt(0)
	v_add_f32_e32 v126, v126, v127
	v_add_f32_e32 v160, v160, v126
	s_nop 1
	v_max_f32_e32 v126, v108, v109
	s_nop 0
	v_max_f32_e32 v127, v112, v113
	v_max3_f32 v126, v106, v107, v126
	v_max3_f32 v127, v110, v111, v127
	v_max3_f32 v126, v126, s51, v127
	s_nop 1
	v_max_f32_e32 v127, v116, v117
	s_nop 0
	v_max_f32_e32 v128, v120, v121
	v_max3_f32 v127, v114, v115, v127
	v_max3_f32 v128, v118, v119, v128
	v_max3_f32 v131, v126, v127, v128
	ds_bpermute_b32 v133, v155, v131
	v_cvt_pk_bf16_f32 v126, v122, v192
	v_cvt_pk_bf16_f32 v127, v123, v193
	v_cvt_pk_bf16_f32 v128, v124, v194
	v_cvt_pk_bf16_f32 v129, v125, v195
	s_waitcnt lgkmcnt(0)
	s_nop 0
	v_max_f32_e32 v131, v131, v133
	ds_bpermute_b32 v133, v176, v131
	v_cvt_pk_bf16_f32 v122, v0, v164
	v_cvt_pk_bf16_f32 v123, v177, v179
	v_cvt_pk_bf16_f32 v124, v130, v132
	v_add_f32_e32 v130, 0x41000000, v165
	s_waitcnt lgkmcnt(0)
	s_nop 0
	v_max_f32_e32 v0, v131, v133
	v_mul_f32_e32 v0, 0x3e16c740, v0
	v_cmp_gt_f32_e32 vcc, v0, v130
	v_cvt_pk_bf16_f32 v125, v196, v168
	s_cbranch_vccz .LBB0_657
	s_nop 0
	v_cndmask_b32_e32 v167, v165, v0, vcc
	v_sub_f32_e32 v0, v165, v167
	v_exp_f32_e32 v0, v0
	v_mov_b32_e32 v165, v167
	v_mul_f32_e32 v161, v161, v0
	v_pk_mul_f32 v[104:105], v[104:105], v[0:1] op_sel_hi:[1,0]
	v_pk_mul_f32 v[102:103], v[102:103], v[0:1] op_sel_hi:[1,0]
	v_pk_mul_f32 v[100:101], v[100:101], v[0:1] op_sel_hi:[1,0]
	v_pk_mul_f32 v[98:99], v[98:99], v[0:1] op_sel_hi:[1,0]
	v_pk_mul_f32 v[96:97], v[96:97], v[0:1] op_sel_hi:[1,0]
	v_pk_mul_f32 v[94:95], v[94:95], v[0:1] op_sel_hi:[1,0]
	v_pk_mul_f32 v[92:93], v[92:93], v[0:1] op_sel_hi:[1,0]
	v_pk_mul_f32 v[90:91], v[90:91], v[0:1] op_sel_hi:[1,0]
	s_branch .LBB0_657

.LBB0_1075:
	s_barrier
	s_waitcnt vmcnt(7)
	ds_write_b128 v167, v[28:31]
	s_waitcnt vmcnt(6)
	ds_write_b128 v168, v[32:35]
	s_waitcnt vmcnt(5)
	ds_write_b128 v169, v[44:47] offset:17408
	s_waitcnt vmcnt(4)
	ds_write_b128 v170, v[48:51] offset:17408
	s_waitcnt lgkmcnt(0)
	s_barrier
	ds_read_b128 v[28:31], v171
	ds_read_b128 v[44:47], v171 offset:1088
	ds_read_b128 v[32:35], v172
	s_add_i32 s47, s45, -1
	ds_read_b128 v[48:51], v172 offset:1088
	s_min_u32 s4, s47, s44
	s_waitcnt lgkmcnt(3)
	v_mfma_f32_16x16x32_bf16 v[28:31], v[28:31], v[4:7], 0
	s_lshl_b32 s54, s4, 6
	s_cmp_lt_u32 s4, 4
	s_cselect_b64 s[48:49], -1, 0
	s_add_i32 s4, s54, 0xffffff00
	s_and_b64 s[52:53], s[48:49], exec
	s_waitcnt lgkmcnt(1)
	v_mfma_f32_16x16x32_bf16 v[128:131], v[32:35], v[8:11], v[28:31]
	s_cselect_b32 s58, s54, s4
	s_cselect_b32 s4, s27, s15
	s_cselect_b32 s54, s26, s14
	v_mfma_f32_16x16x32_bf16 v[28:31], v[44:47], v[4:7], 0
	ds_read_b128 v[44:47], v171 offset:8704
	s_lshl_b64 s[52:53], s[58:59], 11
	s_add_u32 s54, s54, s52
	s_addc_u32 s4, s4, s53
	s_waitcnt lgkmcnt(1)
	v_mfma_f32_16x16x32_bf16 v[124:127], v[48:51], v[8:11], v[28:31]
	ds_read_b128 v[48:51], v172 offset:8704
	s_and_b64 s[48:49], s[48:49], exec
	s_cselect_b32 s49, s36, s24
	s_cselect_b32 s48, s37, s25
	s_add_u32 s52, s49, s52
	s_addc_u32 s53, s48, s53
	s_add_u32 s48, s54, s40
	s_waitcnt lgkmcnt(1)
	v_mfma_f32_16x16x32_bf16 v[44:47], v[44:47], v[4:7], 0
	s_addc_u32 s49, s4, s41
	v_lshl_add_u64 v[2:3], v[152:153], 1, s[48:49]
	v_lshl_add_u64 v[32:33], v[154:155], 1, s[48:49]
	s_add_u32 s48, s52, s40
	v_lshl_add_u64 v[2:3], v[140:141], 1, v[2:3]
	v_lshl_add_u64 v[32:33], v[142:143], 1, v[32:33]
	s_addc_u32 s49, s53, s41
	global_load_dwordx4 v[28:31], v[2:3], off
	s_nop 0
	global_load_dwordx4 v[32:35], v[32:33], off
	v_lshl_add_u64 v[2:3], v[150:151], 1, s[48:49]
	s_waitcnt lgkmcnt(0)
	v_mfma_f32_16x16x32_bf16 v[120:123], v[48:51], v[8:11], v[44:47]
	v_lshl_add_u64 v[2:3], v[144:145], 1, v[2:3]
	ds_read_b128 v[116:119], v171 offset:9792
	ds_read_b128 v[132:135], v172 offset:9792
	v_lshl_add_u64 v[44:45], v[156:157], 1, s[48:49]
	v_lshl_add_u64 v[48:49], v[146:147], 1, v[44:45]
	global_load_dwordx4 v[44:47], v[2:3], off
	s_nop 0
	global_load_dwordx4 v[48:51], v[48:49], off
	s_waitcnt lgkmcnt(1)
	v_mfma_f32_16x16x32_bf16 v[116:119], v[116:119], v[4:7], 0
	s_nop 1
	v_max_f32_e32 v0, v130, v131
	s_waitcnt lgkmcnt(0)
	v_mfma_f32_16x16x32_bf16 v[116:119], v[132:135], v[8:11], v[116:119]
	s_nop 1
	v_max_f32_e32 v2, v126, v127
	v_max3_f32 v0, v128, v129, v0
	v_max3_f32 v2, v124, v125, v2
	v_max3_f32 v0, v0, s51, v2
	s_nop 1
	v_max_f32_e32 v2, v122, v123
	s_nop 1
	v_max_f32_e32 v3, v118, v119
	v_max3_f32 v2, v120, v121, v2
	v_max3_f32 v3, v116, v117, v3
	v_max3_f32 v0, v0, v2, v3
	ds_bpermute_b32 v2, v198, v0
	s_waitcnt lgkmcnt(0)
	s_nop 0
	v_max_f32_e32 v0, v0, v2
	ds_bpermute_b32 v2, v179, v0
	s_waitcnt lgkmcnt(0)
	s_nop 0
	v_max_f32_e32 v0, v0, v2
	v_mul_f32_e32 v0, 0x3e38aa3b, v0
	v_add_f32_e32 v2, 0x41000000, v193
	v_cmp_gt_f32_e32 vcc, v0, v2
	s_cbranch_vccz .LBB0_1077
	s_nop 0
	v_cndmask_b32_e32 v2, v193, v0, vcc
	v_sub_f32_e32 v0, v193, v2
	v_exp_f32_e32 v0, v0
	v_mov_b32_e32 v193, v2
	v_pk_mul_f32 v[114:115], v[114:115], v[0:1] op_sel_hi:[1,0]
	v_pk_mul_f32 v[112:113], v[112:113], v[0:1] op_sel_hi:[1,0]
	v_pk_mul_f32 v[106:107], v[106:107], v[0:1] op_sel_hi:[1,0]
	v_pk_mul_f32 v[104:105], v[104:105], v[0:1] op_sel_hi:[1,0]
	v_pk_mul_f32 v[98:99], v[98:99], v[0:1] op_sel_hi:[1,0]
	v_pk_mul_f32 v[96:97], v[96:97], v[0:1] op_sel_hi:[1,0]
	v_pk_mul_f32 v[90:91], v[90:91], v[0:1] op_sel_hi:[1,0]
	v_pk_mul_f32 v[88:89], v[88:89], v[0:1] op_sel_hi:[1,0]
	v_pk_mul_f32 v[82:83], v[82:83], v[0:1] op_sel_hi:[1,0]
	v_pk_mul_f32 v[80:81], v[80:81], v[0:1] op_sel_hi:[1,0]
	v_pk_mul_f32 v[74:75], v[74:75], v[0:1] op_sel_hi:[1,0]
	v_pk_mul_f32 v[72:73], v[72:73], v[0:1] op_sel_hi:[1,0]
	v_pk_mul_f32 v[66:67], v[66:67], v[0:1] op_sel_hi:[1,0]
	v_pk_mul_f32 v[64:65], v[64:65], v[0:1] op_sel_hi:[1,0]
	v_pk_mul_f32 v[62:63], v[62:63], v[0:1] op_sel_hi:[1,0]
	v_pk_mul_f32 v[60:61], v[60:61], v[0:1] op_sel_hi:[1,0]
	v_mul_f32_e32 v195, v195, v0
.LBB0_1077:
	v_fma_f32 v0, v128, s23, -v193
	v_exp_f32_e32 v3, v0
	v_fma_f32 v0, v129, s23, -v193
	v_exp_f32_e32 v128, v0
	v_fma_f32 v0, v130, s23, -v193
	v_exp_f32_e32 v129, v0
	v_fma_f32 v0, v131, s23, -v193
	v_exp_f32_e32 v130, v0
	v_add_f32_e32 v0, v3, v128
	v_add_f32_e32 v2, v129, v130
	v_add_f32_e32 v0, v0, v2
	v_fma_f32 v2, v124, s23, -v193
	v_exp_f32_e32 v124, v2
	v_fma_f32 v2, v125, s23, -v193
	v_exp_f32_e32 v125, v2
	v_fma_f32 v2, v126, s23, -v193
	v_exp_f32_e32 v126, v2
	v_fma_f32 v2, v127, s23, -v193
	v_exp_f32_e32 v127, v2
	v_add_f32_e32 v2, v124, v125
	v_add_f32_e32 v0, 0, v0
	v_add_f32_e32 v131, v126, v127
	v_add_f32_e32 v2, v2, v131
	v_add_f32_e32 v0, v2, v0
	v_fma_f32 v2, v120, s23, -v193
	v_exp_f32_e32 v131, v2
	v_fma_f32 v2, v121, s23, -v193
	v_exp_f32_e32 v132, v2
	v_fma_f32 v2, v122, s23, -v193
	v_exp_f32_e32 v133, v2
	v_fma_f32 v2, v123, s23, -v193
	v_exp_f32_e32 v134, v2
	v_add_f32_e32 v2, v131, v132
	v_add_f32_e32 v120, v133, v134
	v_add_f32_e32 v2, v2, v120
	v_add_f32_e32 v0, v2, v0
	v_fma_f32 v2, v116, s23, -v193
	v_exp_f32_e32 v135, v2
	v_fma_f32 v2, v117, s23, -v193
	v_exp_f32_e32 v136, v2
	v_fma_f32 v2, v118, s23, -v193
	v_exp_f32_e32 v137, v2
	v_fma_f32 v2, v119, s23, -v193
	v_exp_f32_e32 v119, v2
	v_add_f32_e32 v2, v135, v136
	v_cvt_pk_bf16_f32 v120, v3, v128
	v_cvt_pk_bf16_f32 v121, v129, v130
	v_add_f32_e32 v116, v137, v119
	v_add_f32_e32 v2, v2, v116
	v_cvt_pk_bf16_f32 v122, v124, v125
	v_cvt_pk_bf16_f32 v123, v126, v127
	v_cvt_pk_bf16_f32 v116, v131, v132
	v_cvt_pk_bf16_f32 v117, v133, v134
	v_cvt_pk_bf16_f32 v118, v135, v136
	v_cvt_pk_bf16_f32 v119, v137, v119
	ds_read_b128 v[124:127], v171 offset:128
	ds_read_b128 v[128:131], v173
	s_waitcnt lgkmcnt(1)
	v_mfma_f32_16x16x32_bf16 v[124:127], v[124:127], v[12:15], 0
	ds_read_b128 v[132:135], v173 offset:1088
	ds_read_b128 v[136:139], v173 offset:8704
	v_add_f32_e32 v0, v2, v0
	s_waitcnt lgkmcnt(2)
	v_mfma_f32_16x16x32_bf16 v[124:127], v[128:131], v[16:19], v[124:127]
	ds_read_b128 v[128:131], v171 offset:1216
	ds_bpermute_b32 v2, v198, v0
	ds_read_b128 v[200:203], v173 offset:9792
	s_waitcnt lgkmcnt(2)
	v_mfma_f32_16x16x32_bf16 v[128:131], v[128:131], v[12:15], 0
	s_nop 2
	s_nop 1
	v_max_f32_e32 v3, v126, v127
	v_mfma_f32_16x16x32_bf16 v[128:131], v[132:135], v[16:19], v[128:131]
	ds_read_b128 v[132:135], v171 offset:8832
	v_max3_f32 v3, v124, v125, v3
	s_waitcnt lgkmcnt(2)
	v_add_f32_e32 v0, v0, v2
	s_waitcnt lgkmcnt(0)
	v_mfma_f32_16x16x32_bf16 v[132:135], v[132:135], v[12:15], 0
	s_nop 1
	s_nop 1
	v_max_f32_e32 v196, v130, v131
	v_mfma_f32_16x16x32_bf16 v[132:135], v[136:139], v[16:19], v[132:135]
	ds_read_b128 v[136:139], v171 offset:9920
	v_max3_f32 v196, v128, v129, v196
	v_max3_f32 v3, v3, s51, v196
	s_waitcnt lgkmcnt(0)
	v_mfma_f32_16x16x32_bf16 v[136:139], v[136:139], v[12:15], 0
	s_nop 2
	s_nop 1
	v_max_f32_e32 v196, v134, v135
	v_mfma_f32_16x16x32_bf16 v[136:139], v[200:203], v[16:19], v[136:139]
	v_max3_f32 v196, v132, v133, v196
	ds_bpermute_b32 v2, v179, v0
	s_nop 5
	s_nop 1
	v_max_f32_e32 v197, v138, v139
	v_max3_f32 v197, v136, v137, v197
	v_max3_f32 v3, v3, v196, v197
	ds_bpermute_b32 v196, v198, v3
	s_waitcnt lgkmcnt(0)
	s_nop 0
	v_max_f32_e32 v3, v3, v196
	ds_bpermute_b32 v196, v179, v3
	s_waitcnt lgkmcnt(0)
	s_nop 0
	v_max_f32_e32 v3, v3, v196
	v_mul_f32_e32 v3, 0x3e38aa3b, v3
	v_add_f32_e32 v196, 0x41000000, v161
	v_cmp_gt_f32_e32 vcc, v3, v196
	s_cbranch_vccz .LBB0_1079
	s_nop 0
	v_cndmask_b32_e32 v3, v161, v3, vcc
	v_sub_f32_e32 v161, v161, v3
	v_exp_f32_e32 v196, v161
	v_mov_b32_e32 v161, v3
	v_pk_mul_f32 v[110:111], v[110:111], v[196:197] op_sel_hi:[1,0]
	v_pk_mul_f32 v[108:109], v[108:109], v[196:197] op_sel_hi:[1,0]
	v_pk_mul_f32 v[102:103], v[102:103], v[196:197] op_sel_hi:[1,0]
	v_pk_mul_f32 v[100:101], v[100:101], v[196:197] op_sel_hi:[1,0]
	v_pk_mul_f32 v[94:95], v[94:95], v[196:197] op_sel_hi:[1,0]
	v_pk_mul_f32 v[92:93], v[92:93], v[196:197] op_sel_hi:[1,0]
	v_pk_mul_f32 v[86:87], v[86:87], v[196:197] op_sel_hi:[1,0]
	v_pk_mul_f32 v[84:85], v[84:85], v[196:197] op_sel_hi:[1,0]
	v_pk_mul_f32 v[78:79], v[78:79], v[196:197] op_sel_hi:[1,0]
	v_pk_mul_f32 v[76:77], v[76:77], v[196:197] op_sel_hi:[1,0]
	v_pk_mul_f32 v[70:71], v[70:71], v[196:197] op_sel_hi:[1,0]
	v_pk_mul_f32 v[68:69], v[68:69], v[196:197] op_sel_hi:[1,0]
	v_pk_mul_f32 v[58:59], v[58:59], v[196:197] op_sel_hi:[1,0]
	v_pk_mul_f32 v[56:57], v[56:57], v[196:197] op_sel_hi:[1,0]
	v_pk_mul_f32 v[54:55], v[54:55], v[196:197] op_sel_hi:[1,0]
	v_pk_mul_f32 v[52:53], v[52:53], v[196:197] op_sel_hi:[1,0]
	v_mul_f32_e32 v194, v194, v196
.LBB0_1079:
	v_add_f32_e32 v0, v0, v2
	v_fma_f32 v2, v124, s23, -v161
	v_exp_f32_e32 v124, v2
	v_fma_f32 v2, v125, s23, -v161
	v_exp_f32_e32 v125, v2
	v_fma_f32 v2, v126, s23, -v161
	v_exp_f32_e32 v126, v2
	v_fma_f32 v2, v127, s23, -v161
	v_exp_f32_e32 v127, v2
	v_add_f32_e32 v2, v124, v125
	v_add_f32_e32 v0, v195, v0
	v_add_f32_e32 v3, v126, v127
	v_add_f32_e32 v2, v2, v3
	v_fma_f32 v3, v128, s23, -v161
	v_exp_f32_e32 v195, v3
	v_fma_f32 v3, v129, s23, -v161
	v_exp_f32_e32 v196, v3
	v_fma_f32 v3, v130, s23, -v161
	v_exp_f32_e32 v197, v3
	v_fma_f32 v3, v131, s23, -v161
	v_exp_f32_e32 v131, v3
	v_add_f32_e32 v3, v195, v196
	v_add_f32_e32 v2, 0, v2
	v_add_f32_e32 v128, v197, v131
	v_add_f32_e32 v3, v3, v128
	v_add_f32_e32 v2, v3, v2
	v_fma_f32 v3, v132, s23, -v161
	v_exp_f32_e32 v132, v3
	v_fma_f32 v3, v133, s23, -v161
	v_exp_f32_e32 v133, v3
	v_fma_f32 v3, v134, s23, -v161
	v_exp_f32_e32 v134, v3
	v_fma_f32 v3, v135, s23, -v161
	v_exp_f32_e32 v135, v3
	v_add_f32_e32 v3, v132, v133
	v_add_f32_e32 v128, v134, v135
	v_add_f32_e32 v3, v3, v128
	v_add_f32_e32 v2, v3, v2
	v_fma_f32 v3, v136, s23, -v161
	v_exp_f32_e32 v136, v3
	v_fma_f32 v3, v137, s23, -v161
	v_exp_f32_e32 v137, v3
	v_fma_f32 v3, v138, s23, -v161
	v_exp_f32_e32 v138, v3
	v_fma_f32 v3, v139, s23, -v161
	v_exp_f32_e32 v139, v3
	v_add_f32_e32 v3, v136, v137
	v_add_f32_e32 v128, v138, v139
	v_add_f32_e32 v3, v3, v128
	v_add_f32_e32 v2, v3, v2
	ds_bpermute_b32 v3, v198, v2
	v_cvt_pk_bf16_f32 v128, v124, v125
	v_cvt_pk_bf16_f32 v129, v126, v127
	v_cvt_pk_bf16_f32 v130, v195, v196
	v_cvt_pk_bf16_f32 v131, v197, v131
	s_waitcnt lgkmcnt(0)
	v_add_f32_e32 v2, v2, v3
	ds_bpermute_b32 v3, v179, v2
	v_cvt_pk_bf16_f32 v124, v132, v133
	v_cvt_pk_bf16_f32 v125, v134, v135
	v_cvt_pk_bf16_f32 v126, v136, v137
	v_cvt_pk_bf16_f32 v127, v138, v139
	ds_read_b64_tr_b16 v[134:135], v174 offset:18560
	ds_read_b64_tr_b16 v[132:133], v174 offset:17408
	ds_read_b64_tr_b16 v[136:137], v174 offset:17440
	ds_read_b64_tr_b16 v[138:139], v174 offset:18592
	s_waitcnt lgkmcnt(2)
	v_mfma_f32_16x16x32_bf16 v[112:115], v[132:135], v[120:123], v[112:115]
	v_mfma_f32_16x16x32_bf16 v[108:111], v[132:135], v[128:131], v[108:111]
	ds_read_b64_tr_b16 v[132:133], v174 offset:17472
	ds_read_b64_tr_b16 v[134:135], v174 offset:18624
	s_waitcnt lgkmcnt(0)
	v_mfma_f32_16x16x32_bf16 v[96:99], v[132:135], v[120:123], v[96:99]
	v_mfma_f32_16x16x32_bf16 v[92:95], v[132:135], v[128:131], v[92:95]
	ds_read_b64_tr_b16 v[132:133], v174 offset:17504
	ds_read_b64_tr_b16 v[134:135], v174 offset:18656
	v_mfma_f32_16x16x32_bf16 v[104:107], v[136:139], v[120:123], v[104:107]
	v_mfma_f32_16x16x32_bf16 v[100:103], v[136:139], v[128:131], v[100:103]
	s_waitcnt lgkmcnt(0)
	v_mfma_f32_16x16x32_bf16 v[136:139], v[132:135], v[120:123], v[88:91]
	v_mfma_f32_16x16x32_bf16 v[132:135], v[132:135], v[128:131], v[84:87]
	s_nop 2
	ds_read_b64_tr_b16 v[84:85], v175 offset:17408
	ds_read_b64_tr_b16 v[86:87], v175 offset:18560
	s_waitcnt lgkmcnt(0)
	v_mfma_f32_16x16x32_bf16 v[204:207], v[84:87], v[128:131], v[76:79]
	s_nop 2
	ds_read_b64_tr_b16 v[76:77], v176 offset:17408
	ds_read_b64_tr_b16 v[78:79], v176 offset:18560
	s_waitcnt lgkmcnt(0)
	v_mfma_f32_16x16x32_bf16 v[208:211], v[76:79], v[128:131], v[68:71]
	s_nop 2
	ds_read_b64_tr_b16 v[68:69], v177 offset:17408
	ds_read_b64_tr_b16 v[70:71], v177 offset:18560
	s_waitcnt lgkmcnt(0)
	v_mfma_f32_16x16x32_bf16 v[216:219], v[68:71], v[128:131], v[56:59]
	s_nop 2
	ds_read_b64_tr_b16 v[56:57], v192 offset:17408
	ds_read_b64_tr_b16 v[58:59], v192 offset:18560
	v_mfma_f32_16x16x32_bf16 v[200:203], v[84:87], v[120:123], v[80:83]
	v_mfma_f32_16x16x32_bf16 v[72:75], v[76:79], v[120:123], v[72:75]
	v_mfma_f32_16x16x32_bf16 v[212:215], v[68:71], v[120:123], v[64:67]
	s_waitcnt lgkmcnt(0)
	v_mfma_f32_16x16x32_bf16 v[120:123], v[56:59], v[120:123], v[60:63]
	v_mfma_f32_16x16x32_bf16 v[128:131], v[56:59], v[128:131], v[52:55]
	s_min_u32 s4, s45, s44
	s_nop 1
	ds_read_b64_tr_b16 v[54:55], v174 offset:27776
	ds_read_b64_tr_b16 v[52:53], v174 offset:26624
	ds_read_b64_tr_b16 v[56:57], v174 offset:26656
	ds_read_b64_tr_b16 v[58:59], v174 offset:27808
	s_lshl_b32 s54, s4, 6
	s_cmp_lt_u32 s4, 4
	s_cselect_b64 s[48:49], -1, 0
	s_add_i32 s4, s54, 0xffffff00
	s_and_b64 s[52:53], s[48:49], exec
	s_cselect_b32 s58, s54, s4
	s_cselect_b32 s4, s27, s15
	s_cselect_b32 s54, s26, s14
	s_lshl_b64 s[52:53], s[58:59], 11
	s_add_u32 s54, s54, s52
	s_addc_u32 s4, s4, s53
	s_and_b64 s[48:49], s[48:49], exec
	s_waitcnt lgkmcnt(2)
	v_mfma_f32_16x16x32_bf16 v[68:71], v[52:55], v[116:119], v[112:115]
	s_cselect_b32 s49, s36, s24
	s_cselect_b32 s48, s37, s25
	s_add_u32 s52, s49, s52
	v_mfma_f32_16x16x32_bf16 v[80:83], v[52:55], v[124:127], v[108:111]
	ds_read_b64_tr_b16 v[52:53], v174 offset:26688
	ds_read_b64_tr_b16 v[54:55], v174 offset:27840
	s_addc_u32 s53, s48, s53
	s_add_u32 s48, s54, s40
	s_waitcnt lgkmcnt(2)
	v_mfma_f32_16x16x32_bf16 v[64:67], v[56:59], v[116:119], v[104:107]
	s_addc_u32 s49, s4, s41
	v_mfma_f32_16x16x32_bf16 v[76:79], v[56:59], v[124:127], v[100:103]
	ds_read_b64_tr_b16 v[56:57], v174 offset:26720
	ds_read_b64_tr_b16 v[58:59], v174 offset:27872
	ds_read_b64_tr_b16 v[60:61], v175 offset:26624
	ds_read_b64_tr_b16 v[62:63], v175 offset:27776
	ds_read_b64_tr_b16 v[100:101], v176 offset:26624
	ds_read_b64_tr_b16 v[102:103], v176 offset:27776
	s_waitcnt lgkmcnt(6)
	v_mfma_f32_16x16x32_bf16 v[84:87], v[52:55], v[116:119], v[96:99]
	v_mfma_f32_16x16x32_bf16 v[88:91], v[52:55], v[124:127], v[92:95]
	s_waitcnt lgkmcnt(2)
	v_mfma_f32_16x16x32_bf16 v[92:95], v[60:63], v[116:119], v[200:203]
	v_mfma_f32_16x16x32_bf16 v[96:99], v[60:63], v[124:127], v[204:207]
	s_waitcnt lgkmcnt(0)
	v_mfma_f32_16x16x32_bf16 v[60:63], v[100:103], v[116:119], v[72:75]
	v_mfma_f32_16x16x32_bf16 v[72:75], v[100:103], v[124:127], v[208:211]
	ds_read_b64_tr_b16 v[100:101], v177 offset:26624
	ds_read_b64_tr_b16 v[102:103], v177 offset:27776
	ds_read_b64_tr_b16 v[104:105], v192 offset:26624
	ds_read_b64_tr_b16 v[106:107], v192 offset:27776
	s_waitcnt lgkmcnt(0)
	s_barrier
	s_waitcnt vmcnt(7)
	ds_write_b128 v167, v[24:27]
	s_waitcnt vmcnt(6)
	ds_write_b128 v168, v[20:23]
	s_waitcnt vmcnt(5)
	ds_write_b128 v169, v[36:39] offset:17408
	s_waitcnt vmcnt(4)
	ds_write_b128 v170, v[40:43] offset:17408
	v_lshl_add_u64 v[20:21], v[152:153], 1, s[48:49]
	v_lshl_add_u64 v[20:21], v[140:141], 1, v[20:21]
	s_waitcnt lgkmcnt(0)
	s_barrier
	global_load_dwordx4 v[24:27], v[20:21], off
	v_lshl_add_u64 v[20:21], v[154:155], 1, s[48:49]
	s_add_u32 s48, s52, s40
	s_addc_u32 s49, s53, s41
	v_lshl_add_u64 v[36:37], v[150:151], 1, s[48:49]
	v_lshl_add_u64 v[40:41], v[156:157], 1, s[48:49]
	v_lshl_add_u64 v[20:21], v[142:143], 1, v[20:21]
	v_lshl_add_u64 v[36:37], v[144:145], 1, v[36:37]
	v_lshl_add_u64 v[40:41], v[146:147], 1, v[40:41]
	global_load_dwordx4 v[20:23], v[20:21], off
	v_mfma_f32_16x16x32_bf16 v[52:55], v[56:59], v[116:119], v[136:139]
	global_load_dwordx4 v[36:39], v[36:37], off
	s_nop 0
	global_load_dwordx4 v[40:43], v[40:41], off
	v_mfma_f32_16x16x32_bf16 v[108:111], v[100:103], v[116:119], v[212:215]
	v_mfma_f32_16x16x32_bf16 v[112:115], v[100:103], v[124:127], v[216:219]
	v_mfma_f32_16x16x32_bf16 v[100:103], v[104:107], v[116:119], v[120:123]
	ds_read_b128 v[116:119], v171
	s_nop 1
	ds_read_b128 v[120:123], v172
	s_waitcnt lgkmcnt(1)
	v_mfma_f32_16x16x32_bf16 v[116:119], v[116:119], v[4:7], 0
	s_waitcnt lgkmcnt(0)
	v_mfma_f32_16x16x32_bf16 v[116:119], v[120:123], v[8:11], v[116:119]
	ds_read_b128 v[120:123], v171 offset:1088
	v_mfma_f32_16x16x32_bf16 v[56:59], v[56:59], v[124:127], v[132:135]
	v_mfma_f32_16x16x32_bf16 v[104:107], v[104:107], v[124:127], v[128:131]
	ds_read_b128 v[124:127], v172 offset:1088
	s_nop 0
	ds_read_b128 v[132:135], v172 offset:9792
	s_waitcnt lgkmcnt(2)
	v_mfma_f32_16x16x32_bf16 v[120:123], v[120:123], v[4:7], 0
	ds_read_b128 v[128:131], v172 offset:8704
	s_waitcnt lgkmcnt(2)
	v_mfma_f32_16x16x32_bf16 v[120:123], v[124:127], v[8:11], v[120:123]
	ds_read_b128 v[124:127], v171 offset:8704
	s_waitcnt lgkmcnt(0)
	v_mfma_f32_16x16x32_bf16 v[124:127], v[124:127], v[4:7], 0
	v_mfma_f32_16x16x32_bf16 v[124:127], v[128:131], v[8:11], v[124:127]
	ds_read_b128 v[128:131], v171 offset:9792
	s_waitcnt lgkmcnt(0)
	v_mfma_f32_16x16x32_bf16 v[128:131], v[128:131], v[4:7], 0
	v_mfma_f32_16x16x32_bf16 v[128:131], v[132:135], v[8:11], v[128:131]
	s_nop 1
	v_max_f32_e32 v132, v118, v119
	s_nop 1
	v_max_f32_e32 v133, v122, v123
	v_max3_f32 v132, v116, v117, v132
	v_max3_f32 v133, v120, v121, v133
	v_max3_f32 v132, v132, s51, v133
	s_nop 1
	v_max_f32_e32 v133, v126, v127
	s_nop 1
	v_max_f32_e32 v134, v130, v131
	v_max3_f32 v133, v124, v125, v133
	v_max3_f32 v134, v128, v129, v134
	v_max3_f32 v132, v132, v133, v134
	ds_bpermute_b32 v133, v198, v132
	s_waitcnt lgkmcnt(0)
	s_nop 0
	v_max_f32_e32 v132, v132, v133
	ds_bpermute_b32 v133, v179, v132
	s_waitcnt lgkmcnt(0)
	s_nop 0
	v_max_f32_e32 v132, v132, v133
	v_mul_f32_e32 v132, 0x3e38aa3b, v132
	v_add_f32_e32 v133, 0x41000000, v193
	v_cmp_gt_f32_e32 vcc, v132, v133
	s_cbranch_vccz .LBB0_1081
	s_nop 0
	v_cndmask_b32_e32 v133, v193, v132, vcc
	v_sub_f32_e32 v132, v193, v133
	v_exp_f32_e32 v132, v132
	v_mov_b32_e32 v193, v133
	v_pk_mul_f32 v[70:71], v[70:71], v[132:133] op_sel_hi:[1,0]
	v_pk_mul_f32 v[68:69], v[68:69], v[132:133] op_sel_hi:[1,0]
	v_pk_mul_f32 v[66:67], v[66:67], v[132:133] op_sel_hi:[1,0]
	v_pk_mul_f32 v[64:65], v[64:65], v[132:133] op_sel_hi:[1,0]
	v_pk_mul_f32 v[86:87], v[86:87], v[132:133] op_sel_hi:[1,0]
	v_pk_mul_f32 v[84:85], v[84:85], v[132:133] op_sel_hi:[1,0]
	v_pk_mul_f32 v[54:55], v[54:55], v[132:133] op_sel_hi:[1,0]
	v_pk_mul_f32 v[52:53], v[52:53], v[132:133] op_sel_hi:[1,0]
	v_pk_mul_f32 v[94:95], v[94:95], v[132:133] op_sel_hi:[1,0]
	v_pk_mul_f32 v[92:93], v[92:93], v[132:133] op_sel_hi:[1,0]
	v_pk_mul_f32 v[62:63], v[62:63], v[132:133] op_sel_hi:[1,0]
	v_pk_mul_f32 v[60:61], v[60:61], v[132:133] op_sel_hi:[1,0]
	v_pk_mul_f32 v[110:111], v[110:111], v[132:133] op_sel_hi:[1,0]
	v_pk_mul_f32 v[108:109], v[108:109], v[132:133] op_sel_hi:[1,0]
	v_pk_mul_f32 v[102:103], v[102:103], v[132:133] op_sel_hi:[1,0]
	v_pk_mul_f32 v[100:101], v[100:101], v[132:133] op_sel_hi:[1,0]
	v_mul_f32_e32 v0, v0, v132
	v_xor_b32_e32 v132, 0x80000000, v133
	s_branch .LBB0_1082

.LBB0_1082:
	v_add_f32_e32 v2, v2, v3
	v_fmamk_f32 v3, v116, 0x3e38aa3b, v132
	v_exp_f32_e32 v116, v3
	v_fmamk_f32 v3, v117, 0x3e38aa3b, v132
	v_exp_f32_e32 v117, v3
	v_fmamk_f32 v3, v118, 0x3e38aa3b, v132
	v_exp_f32_e32 v118, v3
	v_fmamk_f32 v3, v119, 0x3e38aa3b, v132
	v_exp_f32_e32 v119, v3
	v_add_f32_e32 v3, v116, v117
	v_fmamk_f32 v120, v120, 0x3e38aa3b, v132
	v_add_f32_e32 v2, v194, v2
	v_add_f32_e32 v133, v118, v119
	v_add_f32_e32 v3, v3, v133
	v_exp_f32_e32 v133, v120
	v_fmamk_f32 v120, v121, 0x3e38aa3b, v132
	v_exp_f32_e32 v134, v120
	v_fmamk_f32 v120, v122, 0x3e38aa3b, v132
	v_exp_f32_e32 v135, v120
	v_fmamk_f32 v120, v123, 0x3e38aa3b, v132
	v_exp_f32_e32 v123, v120
	v_add_f32_e32 v120, v133, v134
	v_add_f32_e32 v3, 0, v3
	v_add_f32_e32 v121, v135, v123
	v_add_f32_e32 v120, v120, v121
	v_add_f32_e32 v3, v120, v3
	v_fmamk_f32 v120, v124, 0x3e38aa3b, v132
	v_exp_f32_e32 v124, v120
	v_fmamk_f32 v120, v125, 0x3e38aa3b, v132
	v_exp_f32_e32 v125, v120
	v_fmamk_f32 v120, v126, 0x3e38aa3b, v132
	v_exp_f32_e32 v126, v120
	v_fmamk_f32 v120, v127, 0x3e38aa3b, v132
	v_exp_f32_e32 v127, v120
	v_add_f32_e32 v120, v124, v125
	v_add_f32_e32 v121, v126, v127
	v_add_f32_e32 v120, v120, v121
	v_add_f32_e32 v3, v120, v3
	v_fmamk_f32 v120, v128, 0x3e38aa3b, v132
	v_exp_f32_e32 v128, v120
	v_fmamk_f32 v120, v129, 0x3e38aa3b, v132
	v_exp_f32_e32 v129, v120
	v_fmamk_f32 v120, v130, 0x3e38aa3b, v132
	v_fmac_f32_e32 v132, 0x3e38aa3b, v131
	v_exp_f32_e32 v130, v120
	v_exp_f32_e32 v131, v132
	v_add_f32_e32 v120, v128, v129
	v_add_f32_e32 v121, v130, v131
	v_add_f32_e32 v120, v120, v121
	v_add_f32_e32 v3, v120, v3
	ds_bpermute_b32 v120, v198, v3
	s_waitcnt lgkmcnt(0)
	v_add_f32_e32 v3, v3, v120
	v_cvt_pk_bf16_f32 v120, v116, v117
	v_cvt_pk_bf16_f32 v121, v118, v119
	v_cvt_pk_bf16_f32 v122, v133, v134
	v_cvt_pk_bf16_f32 v123, v135, v123
	v_cvt_pk_bf16_f32 v116, v124, v125
	v_cvt_pk_bf16_f32 v117, v126, v127
	v_cvt_pk_bf16_f32 v118, v128, v129
	v_cvt_pk_bf16_f32 v119, v130, v131
	ds_read_b128 v[124:127], v171 offset:128
	ds_read_b128 v[128:131], v173
	s_waitcnt lgkmcnt(1)
	v_mfma_f32_16x16x32_bf16 v[124:127], v[124:127], v[12:15], 0
	ds_read_b128 v[132:135], v173 offset:1088
	ds_read_b128 v[136:139], v173 offset:8704
	ds_bpermute_b32 v194, v179, v3
	s_waitcnt lgkmcnt(3)
	v_mfma_f32_16x16x32_bf16 v[124:127], v[128:131], v[16:19], v[124:127]
	ds_read_b128 v[128:131], v171 offset:1216
	ds_read_b128 v[200:203], v173 offset:9792
	s_waitcnt lgkmcnt(1)
	v_mfma_f32_16x16x32_bf16 v[128:131], v[128:131], v[12:15], 0
	s_nop 3
	s_nop 1
	v_max_f32_e32 v195, v126, v127
	v_mfma_f32_16x16x32_bf16 v[128:131], v[132:135], v[16:19], v[128:131]
	ds_read_b128 v[132:135], v171 offset:8832
	v_max3_f32 v195, v124, v125, v195
	s_waitcnt lgkmcnt(0)
	v_mfma_f32_16x16x32_bf16 v[132:135], v[132:135], v[12:15], 0
	s_nop 3
	s_nop 1
	v_max_f32_e32 v196, v130, v131
	v_mfma_f32_16x16x32_bf16 v[132:135], v[136:139], v[16:19], v[132:135]
	ds_read_b128 v[136:139], v171 offset:9920
	v_max3_f32 v196, v128, v129, v196
	v_max3_f32 v195, v195, s51, v196
	s_waitcnt lgkmcnt(0)
	v_mfma_f32_16x16x32_bf16 v[136:139], v[136:139], v[12:15], 0
	s_nop 2
	s_nop 1
	v_max_f32_e32 v196, v134, v135
	v_mfma_f32_16x16x32_bf16 v[136:139], v[200:203], v[16:19], v[136:139]
	v_max3_f32 v196, v132, v133, v196
	s_nop 6
	s_nop 1
	v_max_f32_e32 v197, v138, v139
	v_max3_f32 v197, v136, v137, v197
	v_max3_f32 v195, v195, v196, v197
	ds_bpermute_b32 v196, v198, v195
	s_waitcnt lgkmcnt(0)
	s_nop 0
	v_max_f32_e32 v195, v195, v196
	ds_bpermute_b32 v196, v179, v195
	s_waitcnt lgkmcnt(0)
	s_nop 0
	v_max_f32_e32 v195, v195, v196
	v_mul_f32_e32 v195, 0x3e38aa3b, v195
	v_add_f32_e32 v196, 0x41000000, v161
	v_cmp_gt_f32_e32 vcc, v195, v196
	s_cbranch_vccnz .LBB0_1073
	v_xor_b32_e32 v196, 0x80000000, v161
	s_branch .LBB0_1074
